# all five GEMM phases (proj, merge, out, moe_up, moe_down) use hand-scheduled v_mfma_f32_16x16x32_bf16 mainloops with 16x16 accumulator staging; attention unchanged
# speedup vs baseline: 1.0402x; 1.0007x over previous
.LBB0_507:
	s_andn2_b64 vcc, exec, s[4:5]
	s_mul_hi_u32 s58, s88, 0x1e000
	s_mul_i32 s59, s88, 0x1e000
	s_cbranch_vccnz .LBB0_515
	s_add_u32 s4, s2, s59
	v_lshlrev_b32_e32 v0, 2, v146
	s_addc_u32 s5, s3, s58
	v_and_b32_e32 v147, 0x7c, v0
	v_lshrrev_b32_e32 v0, 4, v146
	s_add_u32 s0, s2, s0
	v_xor_b32_e32 v0, v0, v146
	s_addc_u32 s1, s3, s1
	v_lshlrev_b32_e32 v0, 3, v0
	s_add_u32 s6, s0, 0x4810000
	v_ashrrev_i32_e32 v1, 3, v146
	v_readlane_b32 s10, v254, 10
	v_lshlrev_b32_e32 v192, 1, v147
	v_and_b32_e32 v0, 56, v0
	s_addc_u32 s7, s1, 0
	v_add_u32_e32 v2, s10, v1
	v_readlane_b32 s28, v254, 7
	v_mov_b32_e32 v20, v195
	v_lshl_add_u64 v[128:129], s[2:3], 0, v[192:193]
	s_add_u32 s8, s2, 0x2908e000
	v_add_u32_e32 v1, s28, v1
	v_lshl_or_b32 v192, v2, 10, v0
	s_addc_u32 s9, s3, 0
	v_readfirstlane_b32 s10, v20
	v_lshl_or_b32 v0, v1, 10, v0
	s_lshl_b32 s10, s10, 4
	v_lshlrev_b64 v[132:133], 1, v[192:193]
	v_mov_b32_e32 v1, v193
	v_add_u32_e32 v2, 0x10000, v192
	s_and_b32 s15, s10, 0xfffffc00
	v_lshl_add_u64 v[14:15], s[8:9], 0, v[132:133]
	s_mov_b32 s10, m0
	s_mov_b32 m0, s15
	s_nop 0
	global_load_lds_dwordx4 v[14:15], off
	s_mov_b32 m0, s10
	v_lshlrev_b64 v[130:131], 1, v[0:1]
	v_mov_b32_e32 v3, v193
	v_add_u32_e32 v4, 0x10000, v0
	v_add_u32_e32 v8, 0x20000, v0
	v_add_u32_e32 v12, 0x30000, v0
	s_add_i32 s14, s15, 0x8000
	v_lshl_add_u64 v[0:1], s[6:7], 0, v[130:131]
	s_mov_b32 s10, m0
	s_mov_b32 m0, s14
	s_nop 0
	global_load_lds_dwordx4 v[0:1], off
	s_mov_b32 m0, s10
	v_lshlrev_b64 v[134:135], 1, v[2:3]
	v_mov_b32_e32 v5, v193
	v_add_u32_e32 v6, 0x20000, v192
	v_lshl_add_u64 v[0:1], s[8:9], 0, v[134:135]
	s_add_i32 s16, s15, 0x2000
	s_mov_b32 s10, m0
	s_mov_b32 m0, s16
	s_nop 0
	global_load_lds_dwordx4 v[0:1], off
	s_mov_b32 m0, s10
	v_lshlrev_b64 v[136:137], 1, v[4:5]
	v_mov_b32_e32 v7, v193
	v_lshl_add_u64 v[0:1], s[6:7], 0, v[136:137]
	s_add_i32 s17, s15, 0xa000
	s_mov_b32 s10, m0
	s_mov_b32 m0, s17
	s_nop 0
	global_load_lds_dwordx4 v[0:1], off
	s_mov_b32 m0, s10
	v_lshlrev_b64 v[138:139], 1, v[6:7]
	v_mov_b32_e32 v9, v193
	v_add_u32_e32 v10, 0x30000, v192
	v_lshl_add_u64 v[0:1], s[8:9], 0, v[138:139]
	s_add_i32 s18, s15, 0x4000
	s_mov_b32 s10, m0
	s_mov_b32 m0, s18
	s_nop 0
	global_load_lds_dwordx4 v[0:1], off
	s_mov_b32 m0, s10
	v_lshlrev_b64 v[140:141], 1, v[8:9]
	v_mov_b32_e32 v11, v193
	v_lshl_add_u64 v[0:1], s[6:7], 0, v[140:141]
	s_add_i32 s19, s15, 0xc000
	s_mov_b32 s10, m0
	s_mov_b32 m0, s19
	s_nop 0
	global_load_lds_dwordx4 v[0:1], off
	s_mov_b32 m0, s10
	v_lshlrev_b64 v[142:143], 1, v[10:11]
	v_mov_b32_e32 v13, v193
	v_lshl_add_u64 v[0:1], s[8:9], 0, v[142:143]
	s_add_i32 s20, s15, 0x6000
	s_mov_b32 s8, m0
	s_mov_b32 m0, s20
	s_nop 0
	global_load_lds_dwordx4 v[0:1], off
	s_mov_b32 m0, s8
	v_lshlrev_b64 v[144:145], 1, v[12:13]
	v_lshl_add_u64 v[0:1], s[6:7], 0, v[144:145]
	s_add_i32 s22, s15, 0xe000
	s_mov_b32 s6, m0
	s_mov_b32 m0, s22
	s_nop 0
	global_load_lds_dwordx4 v[0:1], off
	s_mov_b32 m0, s6
	v_and_b32_e32 v17, 31, v20
	v_lshrrev_b32_e32 v0, 1, v20
	s_mov_b32 s6, 0x1ffff80
	v_and_or_b32 v0, v0, s6, v17
	s_add_i32 s7, s15, 0x10000
	s_add_i32 s6, s15, 0x18000
	s_add_u32 s12, s2, 0x2908e080
	v_lshrrev_b32_e32 v16, 5, v20
	v_bfe_u32 v1, v20, 1, 3
	s_addc_u32 s13, s3, 0
	v_lshlrev_b32_e32 v151, 7, v0
	v_bitop3_b32 v0, v16, v1, 1 bitop3:0x6c
	s_add_u32 s24, s0, 0x4810080
	s_waitcnt vmcnt(0)
	s_barrier
	s_mov_b32 s26, m0
	s_add_u32 s10, s2, 0x2908e000
	s_addc_u32 s11, s3, 0
	s_add_u32 s24, s0, 0x4810000
	s_addc_u32 s25, s1, 0
	v_and_b32_e32 v4, 15, v195
	v_lshrrev_b32_e32 v5, 8, v195
	v_lshl_add_u32 v5, v5, 7, v4
	v_lshlrev_b32_e32 v5, 7, v5
	v_bfe_u32 v6, v195, 4, 2
	v_bfe_u32 v7, v195, 1, 3
	v_xor_b32_e32 v6, v6, v7
	v_lshlrev_b32_e32 v6, 4, v6
	v_or_b32_e32 v204, v5, v6
	v_xor_b32_e32 v205, 64, v204
	v_bfe_u32 v7, v195, 6, 2
	v_lshl_add_u32 v7, v7, 6, v4
	v_lshlrev_b32_e32 v7, 7, v7
	v_or_b32_e32 v220, v7, v6
	v_xor_b32_e32 v221, 64, v220
	s_add_u32 s10, s10, 0x80
	s_addc_u32 s11, s11, 0
	s_add_u32 s24, s24, 0x80
	s_addc_u32 s25, s25, 0
	ds_read_b128 v[164:167], v220 offset:32768
	ds_read_b128 v[168:171], v220 offset:34816
	ds_read_b128 v[172:175], v220 offset:36864
	ds_read_b128 v[176:179], v220 offset:38912
	ds_read_b128 v[148:151], v204
	ds_read_b128 v[152:155], v204 offset:2048
	ds_read_b128 v[156:159], v204 offset:4096
	s_add_u32 m0, s15, 0x10000
	s_nop 0
	global_load_lds_dwordx4 v132, s[10:11]
	s_add_u32 m0, s15, 0x18000
	s_nop 0
	global_load_lds_dwordx4 v130, s[24:25]
	s_add_u32 m0, s15, 0x12000
	s_nop 0
	global_load_lds_dwordx4 v134, s[10:11]
	s_add_u32 m0, s15, 0x1a000
	s_nop 0
	global_load_lds_dwordx4 v136, s[24:25]
	s_add_u32 m0, s15, 0x14000
	s_nop 0
	global_load_lds_dwordx4 v138, s[10:11]
	s_add_u32 m0, s15, 0x1c000
	s_nop 0
	global_load_lds_dwordx4 v140, s[24:25]
	s_add_u32 m0, s15, 0x16000
	s_nop 0
	global_load_lds_dwordx4 v142, s[10:11]
	s_add_u32 m0, s15, 0x1e000
	s_nop 0
	global_load_lds_dwordx4 v144, s[24:25]
	s_add_u32 s10, s10, 0x80
	s_addc_u32 s11, s11, 0
	s_add_u32 s24, s24, 0x80
	s_addc_u32 s25, s25, 0
	s_waitcnt lgkmcnt(2)
	v_mfma_f32_16x16x32_bf16 v[0:3], v[148:151], v[164:167], 0
	ds_read_b128 v[160:163], v204 offset:6144
	v_mfma_f32_16x16x32_bf16 v[4:7], v[148:151], v[168:171], 0
	ds_read_b128 v[180:183], v221 offset:32768
	v_mfma_f32_16x16x32_bf16 v[8:11], v[148:151], v[172:175], 0
	v_mfma_f32_16x16x32_bf16 v[12:15], v[148:151], v[176:179], 0
	s_waitcnt lgkmcnt(3)
	v_mfma_f32_16x16x32_bf16 v[16:19], v[152:155], v[164:167], 0
	ds_read_b128 v[148:151], v204 offset:8192
	v_mfma_f32_16x16x32_bf16 v[20:23], v[152:155], v[168:171], 0
	ds_read_b128 v[184:187], v221 offset:34816
	v_mfma_f32_16x16x32_bf16 v[24:27], v[152:155], v[172:175], 0
	v_mfma_f32_16x16x32_bf16 v[28:31], v[152:155], v[176:179], 0
	s_waitcnt lgkmcnt(4)
	v_mfma_f32_16x16x32_bf16 v[32:35], v[156:159], v[164:167], 0
	ds_read_b128 v[152:155], v204 offset:10240
	v_mfma_f32_16x16x32_bf16 v[36:39], v[156:159], v[168:171], 0
	ds_read_b128 v[196:199], v221 offset:36864
	v_mfma_f32_16x16x32_bf16 v[40:43], v[156:159], v[172:175], 0
	v_mfma_f32_16x16x32_bf16 v[44:47], v[156:159], v[176:179], 0
	s_waitcnt lgkmcnt(5)
	v_mfma_f32_16x16x32_bf16 v[48:51], v[160:163], v[164:167], 0
	ds_read_b128 v[156:159], v204 offset:12288
	v_mfma_f32_16x16x32_bf16 v[52:55], v[160:163], v[168:171], 0
	ds_read_b128 v[200:203], v221 offset:38912
	v_mfma_f32_16x16x32_bf16 v[56:59], v[160:163], v[172:175], 0
	v_mfma_f32_16x16x32_bf16 v[60:63], v[160:163], v[176:179], 0
	s_waitcnt lgkmcnt(5)
	v_mfma_f32_16x16x32_bf16 v[64:67], v[148:151], v[164:167], 0
	ds_read_b128 v[160:163], v204 offset:14336
	v_mfma_f32_16x16x32_bf16 v[68:71], v[148:151], v[168:171], 0
	v_mfma_f32_16x16x32_bf16 v[72:75], v[148:151], v[172:175], 0
	v_mfma_f32_16x16x32_bf16 v[76:79], v[148:151], v[176:179], 0
	s_waitcnt lgkmcnt(4)
	v_mfma_f32_16x16x32_bf16 v[80:83], v[152:155], v[164:167], 0
	ds_read_b128 v[148:151], v205
	v_mfma_f32_16x16x32_bf16 v[84:87], v[152:155], v[168:171], 0
	v_mfma_f32_16x16x32_bf16 v[88:91], v[152:155], v[172:175], 0
	v_mfma_f32_16x16x32_bf16 v[92:95], v[152:155], v[176:179], 0
	s_waitcnt lgkmcnt(3)
	v_mfma_f32_16x16x32_bf16 v[96:99], v[156:159], v[164:167], 0
	ds_read_b128 v[152:155], v205 offset:2048
	v_mfma_f32_16x16x32_bf16 v[100:103], v[156:159], v[168:171], 0
	v_mfma_f32_16x16x32_bf16 v[104:107], v[156:159], v[172:175], 0
	v_mfma_f32_16x16x32_bf16 v[108:111], v[156:159], v[176:179], 0
	s_waitcnt lgkmcnt(2)
	v_mfma_f32_16x16x32_bf16 v[112:115], v[160:163], v[164:167], 0
	ds_read_b128 v[156:159], v205 offset:4096
	v_mfma_f32_16x16x32_bf16 v[116:119], v[160:163], v[168:171], 0
	v_mfma_f32_16x16x32_bf16 v[120:123], v[160:163], v[172:175], 0
	v_mfma_f32_16x16x32_bf16 v[124:127], v[160:163], v[176:179], 0
	s_waitcnt lgkmcnt(2)
	v_mfma_f32_16x16x32_bf16 v[0:3], v[148:151], v[180:183], v[0:3]
	ds_read_b128 v[160:163], v205 offset:6144
	v_mfma_f32_16x16x32_bf16 v[4:7], v[148:151], v[184:187], v[4:7]
	v_mfma_f32_16x16x32_bf16 v[8:11], v[148:151], v[196:199], v[8:11]
	v_mfma_f32_16x16x32_bf16 v[12:15], v[148:151], v[200:203], v[12:15]
	s_waitcnt lgkmcnt(2)
	v_mfma_f32_16x16x32_bf16 v[16:19], v[152:155], v[180:183], v[16:19]
	ds_read_b128 v[148:151], v205 offset:8192
	v_mfma_f32_16x16x32_bf16 v[20:23], v[152:155], v[184:187], v[20:23]
	v_mfma_f32_16x16x32_bf16 v[24:27], v[152:155], v[196:199], v[24:27]
	v_mfma_f32_16x16x32_bf16 v[28:31], v[152:155], v[200:203], v[28:31]
	s_waitcnt lgkmcnt(2)
	v_mfma_f32_16x16x32_bf16 v[32:35], v[156:159], v[180:183], v[32:35]
	ds_read_b128 v[152:155], v205 offset:10240
	v_mfma_f32_16x16x32_bf16 v[36:39], v[156:159], v[184:187], v[36:39]
	v_mfma_f32_16x16x32_bf16 v[40:43], v[156:159], v[196:199], v[40:43]
	v_mfma_f32_16x16x32_bf16 v[44:47], v[156:159], v[200:203], v[44:47]
	s_waitcnt lgkmcnt(2)
	v_mfma_f32_16x16x32_bf16 v[48:51], v[160:163], v[180:183], v[48:51]
	ds_read_b128 v[156:159], v205 offset:12288
	v_mfma_f32_16x16x32_bf16 v[52:55], v[160:163], v[184:187], v[52:55]
	v_mfma_f32_16x16x32_bf16 v[56:59], v[160:163], v[196:199], v[56:59]
	v_mfma_f32_16x16x32_bf16 v[60:63], v[160:163], v[200:203], v[60:63]
	s_waitcnt lgkmcnt(2)
	v_mfma_f32_16x16x32_bf16 v[64:67], v[148:151], v[180:183], v[64:67]
	ds_read_b128 v[160:163], v205 offset:14336
	v_mfma_f32_16x16x32_bf16 v[68:71], v[148:151], v[184:187], v[68:71]
	v_mfma_f32_16x16x32_bf16 v[72:75], v[148:151], v[196:199], v[72:75]
	v_mfma_f32_16x16x32_bf16 v[76:79], v[148:151], v[200:203], v[76:79]
	s_waitcnt lgkmcnt(2)
	v_mfma_f32_16x16x32_bf16 v[80:83], v[152:155], v[180:183], v[80:83]
	v_mfma_f32_16x16x32_bf16 v[84:87], v[152:155], v[184:187], v[84:87]
	v_mfma_f32_16x16x32_bf16 v[88:91], v[152:155], v[196:199], v[88:91]
	v_mfma_f32_16x16x32_bf16 v[92:95], v[152:155], v[200:203], v[92:95]
	s_waitcnt lgkmcnt(0)
	s_waitcnt vmcnt(0)
	s_barrier
	v_xor_b32_e32 v204, 0x10000, v204
	v_xor_b32_e32 v205, 0x10000, v205
	v_xor_b32_e32 v220, 0x10000, v220
	v_xor_b32_e32 v221, 0x10000, v221
	v_mfma_f32_16x16x32_bf16 v[96:99], v[156:159], v[180:183], v[96:99]
	ds_read_b128 v[148:151], v204
	ds_read_b128 v[152:155], v204 offset:2048
	s_mov_b32 m0, s15
	v_mfma_f32_16x16x32_bf16 v[100:103], v[156:159], v[184:187], v[100:103]
	global_load_lds_dwordx4 v132, s[10:11]
	v_mfma_f32_16x16x32_bf16 v[104:107], v[156:159], v[196:199], v[104:107]
	ds_read_b128 v[164:167], v220 offset:32768
	ds_read_b128 v[168:171], v220 offset:34816
	s_add_u32 m0, s15, 0x8000
	v_mfma_f32_16x16x32_bf16 v[108:111], v[156:159], v[200:203], v[108:111]
	global_load_lds_dwordx4 v130, s[24:25]
	v_mfma_f32_16x16x32_bf16 v[112:115], v[160:163], v[180:183], v[112:115]
	ds_read_b128 v[156:159], v204 offset:4096
	s_add_u32 m0, s15, 0x2000
	v_mfma_f32_16x16x32_bf16 v[116:119], v[160:163], v[184:187], v[116:119]
	global_load_lds_dwordx4 v134, s[10:11]
	ds_read_b128 v[172:175], v220 offset:36864
	ds_read_b128 v[176:179], v220 offset:38912
	v_mfma_f32_16x16x32_bf16 v[120:123], v[160:163], v[196:199], v[120:123]
	s_add_u32 m0, s15, 0xa000
	v_mfma_f32_16x16x32_bf16 v[124:127], v[160:163], v[200:203], v[124:127]
	global_load_lds_dwordx4 v136, s[24:25]
	s_waitcnt lgkmcnt(4)
	v_mfma_f32_16x16x32_bf16 v[0:3], v[148:151], v[164:167], v[0:3]
	ds_read_b128 v[160:163], v204 offset:6144
	s_waitcnt lgkmcnt(4)
	v_mfma_f32_16x16x32_bf16 v[4:7], v[148:151], v[168:171], v[4:7]
	ds_read_b128 v[180:183], v221 offset:32768
	s_waitcnt lgkmcnt(3)
	v_mfma_f32_16x16x32_bf16 v[8:11], v[148:151], v[172:175], v[8:11]
	s_waitcnt lgkmcnt(2)
	v_mfma_f32_16x16x32_bf16 v[12:15], v[148:151], v[176:179], v[12:15]
	v_mfma_f32_16x16x32_bf16 v[16:19], v[152:155], v[164:167], v[16:19]
	ds_read_b128 v[148:151], v204 offset:8192
	v_mfma_f32_16x16x32_bf16 v[20:23], v[152:155], v[168:171], v[20:23]
	ds_read_b128 v[184:187], v221 offset:34816
	v_mfma_f32_16x16x32_bf16 v[24:27], v[152:155], v[172:175], v[24:27]
	v_mfma_f32_16x16x32_bf16 v[28:31], v[152:155], v[176:179], v[28:31]
	v_mfma_f32_16x16x32_bf16 v[32:35], v[156:159], v[164:167], v[32:35]
	ds_read_b128 v[152:155], v204 offset:10240
	v_mfma_f32_16x16x32_bf16 v[36:39], v[156:159], v[168:171], v[36:39]
	ds_read_b128 v[196:199], v221 offset:36864
	v_mfma_f32_16x16x32_bf16 v[40:43], v[156:159], v[172:175], v[40:43]
	s_add_u32 m0, s15, 0x4000
	v_mfma_f32_16x16x32_bf16 v[44:47], v[156:159], v[176:179], v[44:47]
	global_load_lds_dwordx4 v138, s[10:11]
	s_waitcnt lgkmcnt(5)
	v_mfma_f32_16x16x32_bf16 v[48:51], v[160:163], v[164:167], v[48:51]
	ds_read_b128 v[156:159], v204 offset:12288
	v_mfma_f32_16x16x32_bf16 v[52:55], v[160:163], v[168:171], v[52:55]
	ds_read_b128 v[200:203], v221 offset:38912
	v_mfma_f32_16x16x32_bf16 v[56:59], v[160:163], v[172:175], v[56:59]
	s_add_u32 m0, s15, 0xc000
	v_mfma_f32_16x16x32_bf16 v[60:63], v[160:163], v[176:179], v[60:63]
	global_load_lds_dwordx4 v140, s[24:25]
	s_waitcnt lgkmcnt(5)
	v_mfma_f32_16x16x32_bf16 v[64:67], v[148:151], v[164:167], v[64:67]
	ds_read_b128 v[160:163], v204 offset:14336
	v_mfma_f32_16x16x32_bf16 v[68:71], v[148:151], v[168:171], v[68:71]
	v_mfma_f32_16x16x32_bf16 v[72:75], v[148:151], v[172:175], v[72:75]
	s_add_u32 m0, s15, 0x6000
	v_mfma_f32_16x16x32_bf16 v[76:79], v[148:151], v[176:179], v[76:79]
	global_load_lds_dwordx4 v142, s[10:11]
	s_waitcnt lgkmcnt(4)
	v_mfma_f32_16x16x32_bf16 v[80:83], v[152:155], v[164:167], v[80:83]
	ds_read_b128 v[148:151], v205
	v_mfma_f32_16x16x32_bf16 v[84:87], v[152:155], v[168:171], v[84:87]
	v_mfma_f32_16x16x32_bf16 v[88:91], v[152:155], v[172:175], v[88:91]
	s_add_u32 m0, s15, 0xe000
	v_mfma_f32_16x16x32_bf16 v[92:95], v[152:155], v[176:179], v[92:95]
	global_load_lds_dwordx4 v144, s[24:25]
	s_add_u32 s10, s10, 0x80
	s_addc_u32 s11, s11, 0
	s_add_u32 s24, s24, 0x80
	s_addc_u32 s25, s25, 0
	s_waitcnt lgkmcnt(3)
	v_mfma_f32_16x16x32_bf16 v[96:99], v[156:159], v[164:167], v[96:99]
	ds_read_b128 v[152:155], v205 offset:2048
	v_mfma_f32_16x16x32_bf16 v[100:103], v[156:159], v[168:171], v[100:103]
	v_mfma_f32_16x16x32_bf16 v[104:107], v[156:159], v[172:175], v[104:107]
	v_mfma_f32_16x16x32_bf16 v[108:111], v[156:159], v[176:179], v[108:111]
	s_waitcnt lgkmcnt(2)
	v_mfma_f32_16x16x32_bf16 v[112:115], v[160:163], v[164:167], v[112:115]
	ds_read_b128 v[156:159], v205 offset:4096
	v_mfma_f32_16x16x32_bf16 v[116:119], v[160:163], v[168:171], v[116:119]
	v_mfma_f32_16x16x32_bf16 v[120:123], v[160:163], v[172:175], v[120:123]
	v_mfma_f32_16x16x32_bf16 v[124:127], v[160:163], v[176:179], v[124:127]
	s_waitcnt lgkmcnt(2)
	v_mfma_f32_16x16x32_bf16 v[0:3], v[148:151], v[180:183], v[0:3]
	ds_read_b128 v[160:163], v205 offset:6144
	v_mfma_f32_16x16x32_bf16 v[4:7], v[148:151], v[184:187], v[4:7]
	v_mfma_f32_16x16x32_bf16 v[8:11], v[148:151], v[196:199], v[8:11]
	v_mfma_f32_16x16x32_bf16 v[12:15], v[148:151], v[200:203], v[12:15]
	s_waitcnt lgkmcnt(2)
	v_mfma_f32_16x16x32_bf16 v[16:19], v[152:155], v[180:183], v[16:19]
	ds_read_b128 v[148:151], v205 offset:8192
	v_mfma_f32_16x16x32_bf16 v[20:23], v[152:155], v[184:187], v[20:23]
	v_mfma_f32_16x16x32_bf16 v[24:27], v[152:155], v[196:199], v[24:27]
	v_mfma_f32_16x16x32_bf16 v[28:31], v[152:155], v[200:203], v[28:31]
	s_waitcnt lgkmcnt(2)
	v_mfma_f32_16x16x32_bf16 v[32:35], v[156:159], v[180:183], v[32:35]
	ds_read_b128 v[152:155], v205 offset:10240
	v_mfma_f32_16x16x32_bf16 v[36:39], v[156:159], v[184:187], v[36:39]
	v_mfma_f32_16x16x32_bf16 v[40:43], v[156:159], v[196:199], v[40:43]
	v_mfma_f32_16x16x32_bf16 v[44:47], v[156:159], v[200:203], v[44:47]
	s_waitcnt lgkmcnt(2)
	v_mfma_f32_16x16x32_bf16 v[48:51], v[160:163], v[180:183], v[48:51]
	ds_read_b128 v[156:159], v205 offset:12288
	v_mfma_f32_16x16x32_bf16 v[52:55], v[160:163], v[184:187], v[52:55]
	v_mfma_f32_16x16x32_bf16 v[56:59], v[160:163], v[196:199], v[56:59]
	v_mfma_f32_16x16x32_bf16 v[60:63], v[160:163], v[200:203], v[60:63]
	s_waitcnt lgkmcnt(2)
	v_mfma_f32_16x16x32_bf16 v[64:67], v[148:151], v[180:183], v[64:67]
	ds_read_b128 v[160:163], v205 offset:14336
	v_mfma_f32_16x16x32_bf16 v[68:71], v[148:151], v[184:187], v[68:71]
	v_mfma_f32_16x16x32_bf16 v[72:75], v[148:151], v[196:199], v[72:75]
	v_mfma_f32_16x16x32_bf16 v[76:79], v[148:151], v[200:203], v[76:79]
	s_waitcnt lgkmcnt(2)
	v_mfma_f32_16x16x32_bf16 v[80:83], v[152:155], v[180:183], v[80:83]
	v_mfma_f32_16x16x32_bf16 v[84:87], v[152:155], v[184:187], v[84:87]
	v_mfma_f32_16x16x32_bf16 v[88:91], v[152:155], v[196:199], v[88:91]
	v_mfma_f32_16x16x32_bf16 v[92:95], v[152:155], v[200:203], v[92:95]
	s_waitcnt lgkmcnt(0)
	s_waitcnt vmcnt(0)
	s_barrier
	v_xor_b32_e32 v204, 0x10000, v204
	v_xor_b32_e32 v205, 0x10000, v205
	v_xor_b32_e32 v220, 0x10000, v220
	v_xor_b32_e32 v221, 0x10000, v221
	v_mfma_f32_16x16x32_bf16 v[96:99], v[156:159], v[180:183], v[96:99]
	ds_read_b128 v[148:151], v204
	ds_read_b128 v[152:155], v204 offset:2048
	s_add_u32 m0, s15, 0x10000
	v_mfma_f32_16x16x32_bf16 v[100:103], v[156:159], v[184:187], v[100:103]
	global_load_lds_dwordx4 v132, s[10:11]
	v_mfma_f32_16x16x32_bf16 v[104:107], v[156:159], v[196:199], v[104:107]
	ds_read_b128 v[164:167], v220 offset:32768
	ds_read_b128 v[168:171], v220 offset:34816
	s_add_u32 m0, s15, 0x18000
	v_mfma_f32_16x16x32_bf16 v[108:111], v[156:159], v[200:203], v[108:111]
	global_load_lds_dwordx4 v130, s[24:25]
	v_mfma_f32_16x16x32_bf16 v[112:115], v[160:163], v[180:183], v[112:115]
	ds_read_b128 v[156:159], v204 offset:4096
	s_add_u32 m0, s15, 0x12000
	v_mfma_f32_16x16x32_bf16 v[116:119], v[160:163], v[184:187], v[116:119]
	global_load_lds_dwordx4 v134, s[10:11]
	ds_read_b128 v[172:175], v220 offset:36864
	ds_read_b128 v[176:179], v220 offset:38912
	v_mfma_f32_16x16x32_bf16 v[120:123], v[160:163], v[196:199], v[120:123]
	s_add_u32 m0, s15, 0x1a000
	v_mfma_f32_16x16x32_bf16 v[124:127], v[160:163], v[200:203], v[124:127]
	global_load_lds_dwordx4 v136, s[24:25]
	s_waitcnt lgkmcnt(4)
	v_mfma_f32_16x16x32_bf16 v[0:3], v[148:151], v[164:167], v[0:3]
	ds_read_b128 v[160:163], v204 offset:6144
	s_waitcnt lgkmcnt(4)
	v_mfma_f32_16x16x32_bf16 v[4:7], v[148:151], v[168:171], v[4:7]
	ds_read_b128 v[180:183], v221 offset:32768
	s_waitcnt lgkmcnt(3)
	v_mfma_f32_16x16x32_bf16 v[8:11], v[148:151], v[172:175], v[8:11]
	s_waitcnt lgkmcnt(2)
	v_mfma_f32_16x16x32_bf16 v[12:15], v[148:151], v[176:179], v[12:15]
	v_mfma_f32_16x16x32_bf16 v[16:19], v[152:155], v[164:167], v[16:19]
	ds_read_b128 v[148:151], v204 offset:8192
	v_mfma_f32_16x16x32_bf16 v[20:23], v[152:155], v[168:171], v[20:23]
	ds_read_b128 v[184:187], v221 offset:34816
	v_mfma_f32_16x16x32_bf16 v[24:27], v[152:155], v[172:175], v[24:27]
	v_mfma_f32_16x16x32_bf16 v[28:31], v[152:155], v[176:179], v[28:31]
	v_mfma_f32_16x16x32_bf16 v[32:35], v[156:159], v[164:167], v[32:35]
	ds_read_b128 v[152:155], v204 offset:10240
	v_mfma_f32_16x16x32_bf16 v[36:39], v[156:159], v[168:171], v[36:39]
	ds_read_b128 v[196:199], v221 offset:36864
	v_mfma_f32_16x16x32_bf16 v[40:43], v[156:159], v[172:175], v[40:43]
	s_add_u32 m0, s15, 0x14000
	v_mfma_f32_16x16x32_bf16 v[44:47], v[156:159], v[176:179], v[44:47]
	global_load_lds_dwordx4 v138, s[10:11]
	s_waitcnt lgkmcnt(5)
	v_mfma_f32_16x16x32_bf16 v[48:51], v[160:163], v[164:167], v[48:51]
	ds_read_b128 v[156:159], v204 offset:12288
	v_mfma_f32_16x16x32_bf16 v[52:55], v[160:163], v[168:171], v[52:55]
	ds_read_b128 v[200:203], v221 offset:38912
	v_mfma_f32_16x16x32_bf16 v[56:59], v[160:163], v[172:175], v[56:59]
	s_add_u32 m0, s15, 0x1c000
	v_mfma_f32_16x16x32_bf16 v[60:63], v[160:163], v[176:179], v[60:63]
	global_load_lds_dwordx4 v140, s[24:25]
	s_waitcnt lgkmcnt(5)
	v_mfma_f32_16x16x32_bf16 v[64:67], v[148:151], v[164:167], v[64:67]
	ds_read_b128 v[160:163], v204 offset:14336
	v_mfma_f32_16x16x32_bf16 v[68:71], v[148:151], v[168:171], v[68:71]
	v_mfma_f32_16x16x32_bf16 v[72:75], v[148:151], v[172:175], v[72:75]
	s_add_u32 m0, s15, 0x16000
	v_mfma_f32_16x16x32_bf16 v[76:79], v[148:151], v[176:179], v[76:79]
	global_load_lds_dwordx4 v142, s[10:11]
	s_waitcnt lgkmcnt(4)
	v_mfma_f32_16x16x32_bf16 v[80:83], v[152:155], v[164:167], v[80:83]
	ds_read_b128 v[148:151], v205
	v_mfma_f32_16x16x32_bf16 v[84:87], v[152:155], v[168:171], v[84:87]
	v_mfma_f32_16x16x32_bf16 v[88:91], v[152:155], v[172:175], v[88:91]
	s_add_u32 m0, s15, 0x1e000
	v_mfma_f32_16x16x32_bf16 v[92:95], v[152:155], v[176:179], v[92:95]
	global_load_lds_dwordx4 v144, s[24:25]
	s_add_u32 s10, s10, 0x80
	s_addc_u32 s11, s11, 0
	s_add_u32 s24, s24, 0x80
	s_addc_u32 s25, s25, 0
	s_waitcnt lgkmcnt(3)
	v_mfma_f32_16x16x32_bf16 v[96:99], v[156:159], v[164:167], v[96:99]
	ds_read_b128 v[152:155], v205 offset:2048
	v_mfma_f32_16x16x32_bf16 v[100:103], v[156:159], v[168:171], v[100:103]
	v_mfma_f32_16x16x32_bf16 v[104:107], v[156:159], v[172:175], v[104:107]
	v_mfma_f32_16x16x32_bf16 v[108:111], v[156:159], v[176:179], v[108:111]
	s_waitcnt lgkmcnt(2)
	v_mfma_f32_16x16x32_bf16 v[112:115], v[160:163], v[164:167], v[112:115]
	ds_read_b128 v[156:159], v205 offset:4096
	v_mfma_f32_16x16x32_bf16 v[116:119], v[160:163], v[168:171], v[116:119]
	v_mfma_f32_16x16x32_bf16 v[120:123], v[160:163], v[172:175], v[120:123]
	v_mfma_f32_16x16x32_bf16 v[124:127], v[160:163], v[176:179], v[124:127]
	s_waitcnt lgkmcnt(2)
	v_mfma_f32_16x16x32_bf16 v[0:3], v[148:151], v[180:183], v[0:3]
	ds_read_b128 v[160:163], v205 offset:6144
	v_mfma_f32_16x16x32_bf16 v[4:7], v[148:151], v[184:187], v[4:7]
	v_mfma_f32_16x16x32_bf16 v[8:11], v[148:151], v[196:199], v[8:11]
	v_mfma_f32_16x16x32_bf16 v[12:15], v[148:151], v[200:203], v[12:15]
	s_waitcnt lgkmcnt(2)
	v_mfma_f32_16x16x32_bf16 v[16:19], v[152:155], v[180:183], v[16:19]
	ds_read_b128 v[148:151], v205 offset:8192
	v_mfma_f32_16x16x32_bf16 v[20:23], v[152:155], v[184:187], v[20:23]
	v_mfma_f32_16x16x32_bf16 v[24:27], v[152:155], v[196:199], v[24:27]
	v_mfma_f32_16x16x32_bf16 v[28:31], v[152:155], v[200:203], v[28:31]
	s_waitcnt lgkmcnt(2)
	v_mfma_f32_16x16x32_bf16 v[32:35], v[156:159], v[180:183], v[32:35]
	ds_read_b128 v[152:155], v205 offset:10240
	v_mfma_f32_16x16x32_bf16 v[36:39], v[156:159], v[184:187], v[36:39]
	v_mfma_f32_16x16x32_bf16 v[40:43], v[156:159], v[196:199], v[40:43]
	v_mfma_f32_16x16x32_bf16 v[44:47], v[156:159], v[200:203], v[44:47]
	s_waitcnt lgkmcnt(2)
	v_mfma_f32_16x16x32_bf16 v[48:51], v[160:163], v[180:183], v[48:51]
	ds_read_b128 v[156:159], v205 offset:12288
	v_mfma_f32_16x16x32_bf16 v[52:55], v[160:163], v[184:187], v[52:55]
	v_mfma_f32_16x16x32_bf16 v[56:59], v[160:163], v[196:199], v[56:59]
	v_mfma_f32_16x16x32_bf16 v[60:63], v[160:163], v[200:203], v[60:63]
	s_waitcnt lgkmcnt(2)
	v_mfma_f32_16x16x32_bf16 v[64:67], v[148:151], v[180:183], v[64:67]
	ds_read_b128 v[160:163], v205 offset:14336
	v_mfma_f32_16x16x32_bf16 v[68:71], v[148:151], v[184:187], v[68:71]
	v_mfma_f32_16x16x32_bf16 v[72:75], v[148:151], v[196:199], v[72:75]
	v_mfma_f32_16x16x32_bf16 v[76:79], v[148:151], v[200:203], v[76:79]
	s_waitcnt lgkmcnt(2)
	v_mfma_f32_16x16x32_bf16 v[80:83], v[152:155], v[180:183], v[80:83]
	v_mfma_f32_16x16x32_bf16 v[84:87], v[152:155], v[184:187], v[84:87]
	v_mfma_f32_16x16x32_bf16 v[88:91], v[152:155], v[196:199], v[88:91]
	v_mfma_f32_16x16x32_bf16 v[92:95], v[152:155], v[200:203], v[92:95]
	s_waitcnt lgkmcnt(0)
	s_waitcnt vmcnt(0)
	s_barrier
	v_xor_b32_e32 v204, 0x10000, v204
	v_xor_b32_e32 v205, 0x10000, v205
	v_xor_b32_e32 v220, 0x10000, v220
	v_xor_b32_e32 v221, 0x10000, v221
	v_mfma_f32_16x16x32_bf16 v[96:99], v[156:159], v[180:183], v[96:99]
	ds_read_b128 v[148:151], v204
	ds_read_b128 v[152:155], v204 offset:2048
	s_mov_b32 m0, s15
	v_mfma_f32_16x16x32_bf16 v[100:103], v[156:159], v[184:187], v[100:103]
	global_load_lds_dwordx4 v132, s[10:11]
	v_mfma_f32_16x16x32_bf16 v[104:107], v[156:159], v[196:199], v[104:107]
	ds_read_b128 v[164:167], v220 offset:32768
	ds_read_b128 v[168:171], v220 offset:34816
	s_add_u32 m0, s15, 0x8000
	v_mfma_f32_16x16x32_bf16 v[108:111], v[156:159], v[200:203], v[108:111]
	global_load_lds_dwordx4 v130, s[24:25]
	v_mfma_f32_16x16x32_bf16 v[112:115], v[160:163], v[180:183], v[112:115]
	ds_read_b128 v[156:159], v204 offset:4096
	s_add_u32 m0, s15, 0x2000
	v_mfma_f32_16x16x32_bf16 v[116:119], v[160:163], v[184:187], v[116:119]
	global_load_lds_dwordx4 v134, s[10:11]
	ds_read_b128 v[172:175], v220 offset:36864
	ds_read_b128 v[176:179], v220 offset:38912
	v_mfma_f32_16x16x32_bf16 v[120:123], v[160:163], v[196:199], v[120:123]
	s_add_u32 m0, s15, 0xa000
	v_mfma_f32_16x16x32_bf16 v[124:127], v[160:163], v[200:203], v[124:127]
	global_load_lds_dwordx4 v136, s[24:25]
	s_waitcnt lgkmcnt(4)
	v_mfma_f32_16x16x32_bf16 v[0:3], v[148:151], v[164:167], v[0:3]
	ds_read_b128 v[160:163], v204 offset:6144
	s_waitcnt lgkmcnt(4)
	v_mfma_f32_16x16x32_bf16 v[4:7], v[148:151], v[168:171], v[4:7]
	ds_read_b128 v[180:183], v221 offset:32768
	s_waitcnt lgkmcnt(3)
	v_mfma_f32_16x16x32_bf16 v[8:11], v[148:151], v[172:175], v[8:11]
	s_waitcnt lgkmcnt(2)
	v_mfma_f32_16x16x32_bf16 v[12:15], v[148:151], v[176:179], v[12:15]
	v_mfma_f32_16x16x32_bf16 v[16:19], v[152:155], v[164:167], v[16:19]
	ds_read_b128 v[148:151], v204 offset:8192
	v_mfma_f32_16x16x32_bf16 v[20:23], v[152:155], v[168:171], v[20:23]
	ds_read_b128 v[184:187], v221 offset:34816
	v_mfma_f32_16x16x32_bf16 v[24:27], v[152:155], v[172:175], v[24:27]
	v_mfma_f32_16x16x32_bf16 v[28:31], v[152:155], v[176:179], v[28:31]
	v_mfma_f32_16x16x32_bf16 v[32:35], v[156:159], v[164:167], v[32:35]
	ds_read_b128 v[152:155], v204 offset:10240
	v_mfma_f32_16x16x32_bf16 v[36:39], v[156:159], v[168:171], v[36:39]
	ds_read_b128 v[196:199], v221 offset:36864
	v_mfma_f32_16x16x32_bf16 v[40:43], v[156:159], v[172:175], v[40:43]
	s_add_u32 m0, s15, 0x4000
	v_mfma_f32_16x16x32_bf16 v[44:47], v[156:159], v[176:179], v[44:47]
	global_load_lds_dwordx4 v138, s[10:11]
	s_waitcnt lgkmcnt(5)
	v_mfma_f32_16x16x32_bf16 v[48:51], v[160:163], v[164:167], v[48:51]
	ds_read_b128 v[156:159], v204 offset:12288
	v_mfma_f32_16x16x32_bf16 v[52:55], v[160:163], v[168:171], v[52:55]
	ds_read_b128 v[200:203], v221 offset:38912
	v_mfma_f32_16x16x32_bf16 v[56:59], v[160:163], v[172:175], v[56:59]
	s_add_u32 m0, s15, 0xc000
	v_mfma_f32_16x16x32_bf16 v[60:63], v[160:163], v[176:179], v[60:63]
	global_load_lds_dwordx4 v140, s[24:25]
	s_waitcnt lgkmcnt(5)
	v_mfma_f32_16x16x32_bf16 v[64:67], v[148:151], v[164:167], v[64:67]
	ds_read_b128 v[160:163], v204 offset:14336
	v_mfma_f32_16x16x32_bf16 v[68:71], v[148:151], v[168:171], v[68:71]
	v_mfma_f32_16x16x32_bf16 v[72:75], v[148:151], v[172:175], v[72:75]
	s_add_u32 m0, s15, 0x6000
	v_mfma_f32_16x16x32_bf16 v[76:79], v[148:151], v[176:179], v[76:79]
	global_load_lds_dwordx4 v142, s[10:11]
	s_waitcnt lgkmcnt(4)
	v_mfma_f32_16x16x32_bf16 v[80:83], v[152:155], v[164:167], v[80:83]
	ds_read_b128 v[148:151], v205
	v_mfma_f32_16x16x32_bf16 v[84:87], v[152:155], v[168:171], v[84:87]
	v_mfma_f32_16x16x32_bf16 v[88:91], v[152:155], v[172:175], v[88:91]
	s_add_u32 m0, s15, 0xe000
	v_mfma_f32_16x16x32_bf16 v[92:95], v[152:155], v[176:179], v[92:95]
	global_load_lds_dwordx4 v144, s[24:25]
	s_add_u32 s10, s10, 0x80
	s_addc_u32 s11, s11, 0
	s_add_u32 s24, s24, 0x80
	s_addc_u32 s25, s25, 0
	s_waitcnt lgkmcnt(3)
	v_mfma_f32_16x16x32_bf16 v[96:99], v[156:159], v[164:167], v[96:99]
	ds_read_b128 v[152:155], v205 offset:2048
	v_mfma_f32_16x16x32_bf16 v[100:103], v[156:159], v[168:171], v[100:103]
	v_mfma_f32_16x16x32_bf16 v[104:107], v[156:159], v[172:175], v[104:107]
	v_mfma_f32_16x16x32_bf16 v[108:111], v[156:159], v[176:179], v[108:111]
	s_waitcnt lgkmcnt(2)
	v_mfma_f32_16x16x32_bf16 v[112:115], v[160:163], v[164:167], v[112:115]
	ds_read_b128 v[156:159], v205 offset:4096
	v_mfma_f32_16x16x32_bf16 v[116:119], v[160:163], v[168:171], v[116:119]
	v_mfma_f32_16x16x32_bf16 v[120:123], v[160:163], v[172:175], v[120:123]
	v_mfma_f32_16x16x32_bf16 v[124:127], v[160:163], v[176:179], v[124:127]
	s_waitcnt lgkmcnt(2)
	v_mfma_f32_16x16x32_bf16 v[0:3], v[148:151], v[180:183], v[0:3]
	ds_read_b128 v[160:163], v205 offset:6144
	v_mfma_f32_16x16x32_bf16 v[4:7], v[148:151], v[184:187], v[4:7]
	v_mfma_f32_16x16x32_bf16 v[8:11], v[148:151], v[196:199], v[8:11]
	v_mfma_f32_16x16x32_bf16 v[12:15], v[148:151], v[200:203], v[12:15]
	s_waitcnt lgkmcnt(2)
	v_mfma_f32_16x16x32_bf16 v[16:19], v[152:155], v[180:183], v[16:19]
	ds_read_b128 v[148:151], v205 offset:8192
	v_mfma_f32_16x16x32_bf16 v[20:23], v[152:155], v[184:187], v[20:23]
	v_mfma_f32_16x16x32_bf16 v[24:27], v[152:155], v[196:199], v[24:27]
	v_mfma_f32_16x16x32_bf16 v[28:31], v[152:155], v[200:203], v[28:31]
	s_waitcnt lgkmcnt(2)
	v_mfma_f32_16x16x32_bf16 v[32:35], v[156:159], v[180:183], v[32:35]
	ds_read_b128 v[152:155], v205 offset:10240
	v_mfma_f32_16x16x32_bf16 v[36:39], v[156:159], v[184:187], v[36:39]
	v_mfma_f32_16x16x32_bf16 v[40:43], v[156:159], v[196:199], v[40:43]
	v_mfma_f32_16x16x32_bf16 v[44:47], v[156:159], v[200:203], v[44:47]
	s_waitcnt lgkmcnt(2)
	v_mfma_f32_16x16x32_bf16 v[48:51], v[160:163], v[180:183], v[48:51]
	ds_read_b128 v[156:159], v205 offset:12288
	v_mfma_f32_16x16x32_bf16 v[52:55], v[160:163], v[184:187], v[52:55]
	v_mfma_f32_16x16x32_bf16 v[56:59], v[160:163], v[196:199], v[56:59]
	v_mfma_f32_16x16x32_bf16 v[60:63], v[160:163], v[200:203], v[60:63]
	s_waitcnt lgkmcnt(2)
	v_mfma_f32_16x16x32_bf16 v[64:67], v[148:151], v[180:183], v[64:67]
	ds_read_b128 v[160:163], v205 offset:14336
	v_mfma_f32_16x16x32_bf16 v[68:71], v[148:151], v[184:187], v[68:71]
	v_mfma_f32_16x16x32_bf16 v[72:75], v[148:151], v[196:199], v[72:75]
	v_mfma_f32_16x16x32_bf16 v[76:79], v[148:151], v[200:203], v[76:79]
	s_waitcnt lgkmcnt(2)
	v_mfma_f32_16x16x32_bf16 v[80:83], v[152:155], v[180:183], v[80:83]
	v_mfma_f32_16x16x32_bf16 v[84:87], v[152:155], v[184:187], v[84:87]
	v_mfma_f32_16x16x32_bf16 v[88:91], v[152:155], v[196:199], v[88:91]
	v_mfma_f32_16x16x32_bf16 v[92:95], v[152:155], v[200:203], v[92:95]
	s_waitcnt lgkmcnt(0)
	s_waitcnt vmcnt(0)
	s_barrier
	v_xor_b32_e32 v204, 0x10000, v204
	v_xor_b32_e32 v205, 0x10000, v205
	v_xor_b32_e32 v220, 0x10000, v220
	v_xor_b32_e32 v221, 0x10000, v221
	v_mfma_f32_16x16x32_bf16 v[96:99], v[156:159], v[180:183], v[96:99]
	ds_read_b128 v[148:151], v204
	ds_read_b128 v[152:155], v204 offset:2048
	s_add_u32 m0, s15, 0x10000
	v_mfma_f32_16x16x32_bf16 v[100:103], v[156:159], v[184:187], v[100:103]
	global_load_lds_dwordx4 v132, s[10:11]
	v_mfma_f32_16x16x32_bf16 v[104:107], v[156:159], v[196:199], v[104:107]
	ds_read_b128 v[164:167], v220 offset:32768
	ds_read_b128 v[168:171], v220 offset:34816
	s_add_u32 m0, s15, 0x18000
	v_mfma_f32_16x16x32_bf16 v[108:111], v[156:159], v[200:203], v[108:111]
	global_load_lds_dwordx4 v130, s[24:25]
	v_mfma_f32_16x16x32_bf16 v[112:115], v[160:163], v[180:183], v[112:115]
	ds_read_b128 v[156:159], v204 offset:4096
	s_add_u32 m0, s15, 0x12000
	v_mfma_f32_16x16x32_bf16 v[116:119], v[160:163], v[184:187], v[116:119]
	global_load_lds_dwordx4 v134, s[10:11]
	ds_read_b128 v[172:175], v220 offset:36864
	ds_read_b128 v[176:179], v220 offset:38912
	v_mfma_f32_16x16x32_bf16 v[120:123], v[160:163], v[196:199], v[120:123]
	s_add_u32 m0, s15, 0x1a000
	v_mfma_f32_16x16x32_bf16 v[124:127], v[160:163], v[200:203], v[124:127]
	global_load_lds_dwordx4 v136, s[24:25]
	s_waitcnt lgkmcnt(4)
	v_mfma_f32_16x16x32_bf16 v[0:3], v[148:151], v[164:167], v[0:3]
	ds_read_b128 v[160:163], v204 offset:6144
	s_waitcnt lgkmcnt(4)
	v_mfma_f32_16x16x32_bf16 v[4:7], v[148:151], v[168:171], v[4:7]
	ds_read_b128 v[180:183], v221 offset:32768
	s_waitcnt lgkmcnt(3)
	v_mfma_f32_16x16x32_bf16 v[8:11], v[148:151], v[172:175], v[8:11]
	s_waitcnt lgkmcnt(2)
	v_mfma_f32_16x16x32_bf16 v[12:15], v[148:151], v[176:179], v[12:15]
	v_mfma_f32_16x16x32_bf16 v[16:19], v[152:155], v[164:167], v[16:19]
	ds_read_b128 v[148:151], v204 offset:8192
	v_mfma_f32_16x16x32_bf16 v[20:23], v[152:155], v[168:171], v[20:23]
	ds_read_b128 v[184:187], v221 offset:34816
	v_mfma_f32_16x16x32_bf16 v[24:27], v[152:155], v[172:175], v[24:27]
	v_mfma_f32_16x16x32_bf16 v[28:31], v[152:155], v[176:179], v[28:31]
	v_mfma_f32_16x16x32_bf16 v[32:35], v[156:159], v[164:167], v[32:35]
	ds_read_b128 v[152:155], v204 offset:10240
	v_mfma_f32_16x16x32_bf16 v[36:39], v[156:159], v[168:171], v[36:39]
	ds_read_b128 v[196:199], v221 offset:36864
	v_mfma_f32_16x16x32_bf16 v[40:43], v[156:159], v[172:175], v[40:43]
	s_add_u32 m0, s15, 0x14000
	v_mfma_f32_16x16x32_bf16 v[44:47], v[156:159], v[176:179], v[44:47]
	global_load_lds_dwordx4 v138, s[10:11]
	s_waitcnt lgkmcnt(5)
	v_mfma_f32_16x16x32_bf16 v[48:51], v[160:163], v[164:167], v[48:51]
	ds_read_b128 v[156:159], v204 offset:12288
	v_mfma_f32_16x16x32_bf16 v[52:55], v[160:163], v[168:171], v[52:55]
	ds_read_b128 v[200:203], v221 offset:38912
	v_mfma_f32_16x16x32_bf16 v[56:59], v[160:163], v[172:175], v[56:59]
	s_add_u32 m0, s15, 0x1c000
	v_mfma_f32_16x16x32_bf16 v[60:63], v[160:163], v[176:179], v[60:63]
	global_load_lds_dwordx4 v140, s[24:25]
	s_waitcnt lgkmcnt(5)
	v_mfma_f32_16x16x32_bf16 v[64:67], v[148:151], v[164:167], v[64:67]
	ds_read_b128 v[160:163], v204 offset:14336
	v_mfma_f32_16x16x32_bf16 v[68:71], v[148:151], v[168:171], v[68:71]
	v_mfma_f32_16x16x32_bf16 v[72:75], v[148:151], v[172:175], v[72:75]
	s_add_u32 m0, s15, 0x16000
	v_mfma_f32_16x16x32_bf16 v[76:79], v[148:151], v[176:179], v[76:79]
	global_load_lds_dwordx4 v142, s[10:11]
	s_waitcnt lgkmcnt(4)
	v_mfma_f32_16x16x32_bf16 v[80:83], v[152:155], v[164:167], v[80:83]
	ds_read_b128 v[148:151], v205
	v_mfma_f32_16x16x32_bf16 v[84:87], v[152:155], v[168:171], v[84:87]
	v_mfma_f32_16x16x32_bf16 v[88:91], v[152:155], v[172:175], v[88:91]
	s_add_u32 m0, s15, 0x1e000
	v_mfma_f32_16x16x32_bf16 v[92:95], v[152:155], v[176:179], v[92:95]
	global_load_lds_dwordx4 v144, s[24:25]
	s_add_u32 s10, s10, 0x80
	s_addc_u32 s11, s11, 0
	s_add_u32 s24, s24, 0x80
	s_addc_u32 s25, s25, 0
	s_waitcnt lgkmcnt(3)
	v_mfma_f32_16x16x32_bf16 v[96:99], v[156:159], v[164:167], v[96:99]
	ds_read_b128 v[152:155], v205 offset:2048
	v_mfma_f32_16x16x32_bf16 v[100:103], v[156:159], v[168:171], v[100:103]
	v_mfma_f32_16x16x32_bf16 v[104:107], v[156:159], v[172:175], v[104:107]
	v_mfma_f32_16x16x32_bf16 v[108:111], v[156:159], v[176:179], v[108:111]
	s_waitcnt lgkmcnt(2)
	v_mfma_f32_16x16x32_bf16 v[112:115], v[160:163], v[164:167], v[112:115]
	ds_read_b128 v[156:159], v205 offset:4096
	v_mfma_f32_16x16x32_bf16 v[116:119], v[160:163], v[168:171], v[116:119]
	v_mfma_f32_16x16x32_bf16 v[120:123], v[160:163], v[172:175], v[120:123]
	v_mfma_f32_16x16x32_bf16 v[124:127], v[160:163], v[176:179], v[124:127]
	s_waitcnt lgkmcnt(2)
	v_mfma_f32_16x16x32_bf16 v[0:3], v[148:151], v[180:183], v[0:3]
	ds_read_b128 v[160:163], v205 offset:6144
	v_mfma_f32_16x16x32_bf16 v[4:7], v[148:151], v[184:187], v[4:7]
	v_mfma_f32_16x16x32_bf16 v[8:11], v[148:151], v[196:199], v[8:11]
	v_mfma_f32_16x16x32_bf16 v[12:15], v[148:151], v[200:203], v[12:15]
	s_waitcnt lgkmcnt(2)
	v_mfma_f32_16x16x32_bf16 v[16:19], v[152:155], v[180:183], v[16:19]
	ds_read_b128 v[148:151], v205 offset:8192
	v_mfma_f32_16x16x32_bf16 v[20:23], v[152:155], v[184:187], v[20:23]
	v_mfma_f32_16x16x32_bf16 v[24:27], v[152:155], v[196:199], v[24:27]
	v_mfma_f32_16x16x32_bf16 v[28:31], v[152:155], v[200:203], v[28:31]
	s_waitcnt lgkmcnt(2)
	v_mfma_f32_16x16x32_bf16 v[32:35], v[156:159], v[180:183], v[32:35]
	ds_read_b128 v[152:155], v205 offset:10240
	v_mfma_f32_16x16x32_bf16 v[36:39], v[156:159], v[184:187], v[36:39]
	v_mfma_f32_16x16x32_bf16 v[40:43], v[156:159], v[196:199], v[40:43]
	v_mfma_f32_16x16x32_bf16 v[44:47], v[156:159], v[200:203], v[44:47]
	s_waitcnt lgkmcnt(2)
	v_mfma_f32_16x16x32_bf16 v[48:51], v[160:163], v[180:183], v[48:51]
	ds_read_b128 v[156:159], v205 offset:12288
	v_mfma_f32_16x16x32_bf16 v[52:55], v[160:163], v[184:187], v[52:55]
	v_mfma_f32_16x16x32_bf16 v[56:59], v[160:163], v[196:199], v[56:59]
	v_mfma_f32_16x16x32_bf16 v[60:63], v[160:163], v[200:203], v[60:63]
	s_waitcnt lgkmcnt(2)
	v_mfma_f32_16x16x32_bf16 v[64:67], v[148:151], v[180:183], v[64:67]
	ds_read_b128 v[160:163], v205 offset:14336
	v_mfma_f32_16x16x32_bf16 v[68:71], v[148:151], v[184:187], v[68:71]
	v_mfma_f32_16x16x32_bf16 v[72:75], v[148:151], v[196:199], v[72:75]
	v_mfma_f32_16x16x32_bf16 v[76:79], v[148:151], v[200:203], v[76:79]
	s_waitcnt lgkmcnt(2)
	v_mfma_f32_16x16x32_bf16 v[80:83], v[152:155], v[180:183], v[80:83]
	v_mfma_f32_16x16x32_bf16 v[84:87], v[152:155], v[184:187], v[84:87]
	v_mfma_f32_16x16x32_bf16 v[88:91], v[152:155], v[196:199], v[88:91]
	v_mfma_f32_16x16x32_bf16 v[92:95], v[152:155], v[200:203], v[92:95]
	s_waitcnt lgkmcnt(0)
	s_waitcnt vmcnt(0)
	s_barrier
	v_xor_b32_e32 v204, 0x10000, v204
	v_xor_b32_e32 v205, 0x10000, v205
	v_xor_b32_e32 v220, 0x10000, v220
	v_xor_b32_e32 v221, 0x10000, v221
	v_mfma_f32_16x16x32_bf16 v[96:99], v[156:159], v[180:183], v[96:99]
	ds_read_b128 v[148:151], v204
	ds_read_b128 v[152:155], v204 offset:2048
	s_mov_b32 m0, s15
	v_mfma_f32_16x16x32_bf16 v[100:103], v[156:159], v[184:187], v[100:103]
	global_load_lds_dwordx4 v132, s[10:11]
	v_mfma_f32_16x16x32_bf16 v[104:107], v[156:159], v[196:199], v[104:107]
	ds_read_b128 v[164:167], v220 offset:32768
	ds_read_b128 v[168:171], v220 offset:34816
	s_add_u32 m0, s15, 0x8000
	v_mfma_f32_16x16x32_bf16 v[108:111], v[156:159], v[200:203], v[108:111]
	global_load_lds_dwordx4 v130, s[24:25]
	v_mfma_f32_16x16x32_bf16 v[112:115], v[160:163], v[180:183], v[112:115]
	ds_read_b128 v[156:159], v204 offset:4096
	s_add_u32 m0, s15, 0x2000
	v_mfma_f32_16x16x32_bf16 v[116:119], v[160:163], v[184:187], v[116:119]
	global_load_lds_dwordx4 v134, s[10:11]
	ds_read_b128 v[172:175], v220 offset:36864
	ds_read_b128 v[176:179], v220 offset:38912
	v_mfma_f32_16x16x32_bf16 v[120:123], v[160:163], v[196:199], v[120:123]
	s_add_u32 m0, s15, 0xa000
	v_mfma_f32_16x16x32_bf16 v[124:127], v[160:163], v[200:203], v[124:127]
	global_load_lds_dwordx4 v136, s[24:25]
	s_waitcnt lgkmcnt(4)
	v_mfma_f32_16x16x32_bf16 v[0:3], v[148:151], v[164:167], v[0:3]
	ds_read_b128 v[160:163], v204 offset:6144
	s_waitcnt lgkmcnt(4)
	v_mfma_f32_16x16x32_bf16 v[4:7], v[148:151], v[168:171], v[4:7]
	ds_read_b128 v[180:183], v221 offset:32768
	s_waitcnt lgkmcnt(3)
	v_mfma_f32_16x16x32_bf16 v[8:11], v[148:151], v[172:175], v[8:11]
	s_waitcnt lgkmcnt(2)
	v_mfma_f32_16x16x32_bf16 v[12:15], v[148:151], v[176:179], v[12:15]
	v_mfma_f32_16x16x32_bf16 v[16:19], v[152:155], v[164:167], v[16:19]
	ds_read_b128 v[148:151], v204 offset:8192
	v_mfma_f32_16x16x32_bf16 v[20:23], v[152:155], v[168:171], v[20:23]
	ds_read_b128 v[184:187], v221 offset:34816
	v_mfma_f32_16x16x32_bf16 v[24:27], v[152:155], v[172:175], v[24:27]
	v_mfma_f32_16x16x32_bf16 v[28:31], v[152:155], v[176:179], v[28:31]
	v_mfma_f32_16x16x32_bf16 v[32:35], v[156:159], v[164:167], v[32:35]
	ds_read_b128 v[152:155], v204 offset:10240
	v_mfma_f32_16x16x32_bf16 v[36:39], v[156:159], v[168:171], v[36:39]
	ds_read_b128 v[196:199], v221 offset:36864
	v_mfma_f32_16x16x32_bf16 v[40:43], v[156:159], v[172:175], v[40:43]
	s_add_u32 m0, s15, 0x4000
	v_mfma_f32_16x16x32_bf16 v[44:47], v[156:159], v[176:179], v[44:47]
	global_load_lds_dwordx4 v138, s[10:11]
	s_waitcnt lgkmcnt(5)
	v_mfma_f32_16x16x32_bf16 v[48:51], v[160:163], v[164:167], v[48:51]
	ds_read_b128 v[156:159], v204 offset:12288
	v_mfma_f32_16x16x32_bf16 v[52:55], v[160:163], v[168:171], v[52:55]
	ds_read_b128 v[200:203], v221 offset:38912
	v_mfma_f32_16x16x32_bf16 v[56:59], v[160:163], v[172:175], v[56:59]
	s_add_u32 m0, s15, 0xc000
	v_mfma_f32_16x16x32_bf16 v[60:63], v[160:163], v[176:179], v[60:63]
	global_load_lds_dwordx4 v140, s[24:25]
	s_waitcnt lgkmcnt(5)
	v_mfma_f32_16x16x32_bf16 v[64:67], v[148:151], v[164:167], v[64:67]
	ds_read_b128 v[160:163], v204 offset:14336
	v_mfma_f32_16x16x32_bf16 v[68:71], v[148:151], v[168:171], v[68:71]
	v_mfma_f32_16x16x32_bf16 v[72:75], v[148:151], v[172:175], v[72:75]
	s_add_u32 m0, s15, 0x6000
	v_mfma_f32_16x16x32_bf16 v[76:79], v[148:151], v[176:179], v[76:79]
	global_load_lds_dwordx4 v142, s[10:11]
	s_waitcnt lgkmcnt(4)
	v_mfma_f32_16x16x32_bf16 v[80:83], v[152:155], v[164:167], v[80:83]
	ds_read_b128 v[148:151], v205
	v_mfma_f32_16x16x32_bf16 v[84:87], v[152:155], v[168:171], v[84:87]
	v_mfma_f32_16x16x32_bf16 v[88:91], v[152:155], v[172:175], v[88:91]
	s_add_u32 m0, s15, 0xe000
	v_mfma_f32_16x16x32_bf16 v[92:95], v[152:155], v[176:179], v[92:95]
	global_load_lds_dwordx4 v144, s[24:25]
	s_add_u32 s10, s10, 0x80
	s_addc_u32 s11, s11, 0
	s_add_u32 s24, s24, 0x80
	s_addc_u32 s25, s25, 0
	s_waitcnt lgkmcnt(3)
	v_mfma_f32_16x16x32_bf16 v[96:99], v[156:159], v[164:167], v[96:99]
	ds_read_b128 v[152:155], v205 offset:2048
	v_mfma_f32_16x16x32_bf16 v[100:103], v[156:159], v[168:171], v[100:103]
	v_mfma_f32_16x16x32_bf16 v[104:107], v[156:159], v[172:175], v[104:107]
	v_mfma_f32_16x16x32_bf16 v[108:111], v[156:159], v[176:179], v[108:111]
	s_waitcnt lgkmcnt(2)
	v_mfma_f32_16x16x32_bf16 v[112:115], v[160:163], v[164:167], v[112:115]
	ds_read_b128 v[156:159], v205 offset:4096
	v_mfma_f32_16x16x32_bf16 v[116:119], v[160:163], v[168:171], v[116:119]
	v_mfma_f32_16x16x32_bf16 v[120:123], v[160:163], v[172:175], v[120:123]
	v_mfma_f32_16x16x32_bf16 v[124:127], v[160:163], v[176:179], v[124:127]
	s_waitcnt lgkmcnt(2)
	v_mfma_f32_16x16x32_bf16 v[0:3], v[148:151], v[180:183], v[0:3]
	ds_read_b128 v[160:163], v205 offset:6144
	v_mfma_f32_16x16x32_bf16 v[4:7], v[148:151], v[184:187], v[4:7]
	v_mfma_f32_16x16x32_bf16 v[8:11], v[148:151], v[196:199], v[8:11]
	v_mfma_f32_16x16x32_bf16 v[12:15], v[148:151], v[200:203], v[12:15]
	s_waitcnt lgkmcnt(2)
	v_mfma_f32_16x16x32_bf16 v[16:19], v[152:155], v[180:183], v[16:19]
	ds_read_b128 v[148:151], v205 offset:8192
	v_mfma_f32_16x16x32_bf16 v[20:23], v[152:155], v[184:187], v[20:23]
	v_mfma_f32_16x16x32_bf16 v[24:27], v[152:155], v[196:199], v[24:27]
	v_mfma_f32_16x16x32_bf16 v[28:31], v[152:155], v[200:203], v[28:31]
	s_waitcnt lgkmcnt(2)
	v_mfma_f32_16x16x32_bf16 v[32:35], v[156:159], v[180:183], v[32:35]
	ds_read_b128 v[152:155], v205 offset:10240
	v_mfma_f32_16x16x32_bf16 v[36:39], v[156:159], v[184:187], v[36:39]
	v_mfma_f32_16x16x32_bf16 v[40:43], v[156:159], v[196:199], v[40:43]
	v_mfma_f32_16x16x32_bf16 v[44:47], v[156:159], v[200:203], v[44:47]
	s_waitcnt lgkmcnt(2)
	v_mfma_f32_16x16x32_bf16 v[48:51], v[160:163], v[180:183], v[48:51]
	ds_read_b128 v[156:159], v205 offset:12288
	v_mfma_f32_16x16x32_bf16 v[52:55], v[160:163], v[184:187], v[52:55]
	v_mfma_f32_16x16x32_bf16 v[56:59], v[160:163], v[196:199], v[56:59]
	v_mfma_f32_16x16x32_bf16 v[60:63], v[160:163], v[200:203], v[60:63]
	s_waitcnt lgkmcnt(2)
	v_mfma_f32_16x16x32_bf16 v[64:67], v[148:151], v[180:183], v[64:67]
	ds_read_b128 v[160:163], v205 offset:14336
	v_mfma_f32_16x16x32_bf16 v[68:71], v[148:151], v[184:187], v[68:71]
	v_mfma_f32_16x16x32_bf16 v[72:75], v[148:151], v[196:199], v[72:75]
	v_mfma_f32_16x16x32_bf16 v[76:79], v[148:151], v[200:203], v[76:79]
	s_waitcnt lgkmcnt(2)
	v_mfma_f32_16x16x32_bf16 v[80:83], v[152:155], v[180:183], v[80:83]
	v_mfma_f32_16x16x32_bf16 v[84:87], v[152:155], v[184:187], v[84:87]
	v_mfma_f32_16x16x32_bf16 v[88:91], v[152:155], v[196:199], v[88:91]
	v_mfma_f32_16x16x32_bf16 v[92:95], v[152:155], v[200:203], v[92:95]
	s_waitcnt lgkmcnt(0)
	s_waitcnt vmcnt(0)
	s_barrier
	v_xor_b32_e32 v204, 0x10000, v204
	v_xor_b32_e32 v205, 0x10000, v205
	v_xor_b32_e32 v220, 0x10000, v220
	v_xor_b32_e32 v221, 0x10000, v221
	v_mfma_f32_16x16x32_bf16 v[96:99], v[156:159], v[180:183], v[96:99]
	ds_read_b128 v[148:151], v204
	ds_read_b128 v[152:155], v204 offset:2048
	s_add_u32 m0, s15, 0x10000
	v_mfma_f32_16x16x32_bf16 v[100:103], v[156:159], v[184:187], v[100:103]
	global_load_lds_dwordx4 v132, s[10:11]
	v_mfma_f32_16x16x32_bf16 v[104:107], v[156:159], v[196:199], v[104:107]
	ds_read_b128 v[164:167], v220 offset:32768
	ds_read_b128 v[168:171], v220 offset:34816
	s_add_u32 m0, s15, 0x18000
	v_mfma_f32_16x16x32_bf16 v[108:111], v[156:159], v[200:203], v[108:111]
	global_load_lds_dwordx4 v130, s[24:25]
	v_mfma_f32_16x16x32_bf16 v[112:115], v[160:163], v[180:183], v[112:115]
	ds_read_b128 v[156:159], v204 offset:4096
	s_add_u32 m0, s15, 0x12000
	v_mfma_f32_16x16x32_bf16 v[116:119], v[160:163], v[184:187], v[116:119]
	global_load_lds_dwordx4 v134, s[10:11]
	ds_read_b128 v[172:175], v220 offset:36864
	ds_read_b128 v[176:179], v220 offset:38912
	v_mfma_f32_16x16x32_bf16 v[120:123], v[160:163], v[196:199], v[120:123]
	s_add_u32 m0, s15, 0x1a000
	v_mfma_f32_16x16x32_bf16 v[124:127], v[160:163], v[200:203], v[124:127]
	global_load_lds_dwordx4 v136, s[24:25]
	s_waitcnt lgkmcnt(4)
	v_mfma_f32_16x16x32_bf16 v[0:3], v[148:151], v[164:167], v[0:3]
	ds_read_b128 v[160:163], v204 offset:6144
	s_waitcnt lgkmcnt(4)
	v_mfma_f32_16x16x32_bf16 v[4:7], v[148:151], v[168:171], v[4:7]
	ds_read_b128 v[180:183], v221 offset:32768
	s_waitcnt lgkmcnt(3)
	v_mfma_f32_16x16x32_bf16 v[8:11], v[148:151], v[172:175], v[8:11]
	s_waitcnt lgkmcnt(2)
	v_mfma_f32_16x16x32_bf16 v[12:15], v[148:151], v[176:179], v[12:15]
	v_mfma_f32_16x16x32_bf16 v[16:19], v[152:155], v[164:167], v[16:19]
	ds_read_b128 v[148:151], v204 offset:8192
	v_mfma_f32_16x16x32_bf16 v[20:23], v[152:155], v[168:171], v[20:23]
	ds_read_b128 v[184:187], v221 offset:34816
	v_mfma_f32_16x16x32_bf16 v[24:27], v[152:155], v[172:175], v[24:27]
	v_mfma_f32_16x16x32_bf16 v[28:31], v[152:155], v[176:179], v[28:31]
	v_mfma_f32_16x16x32_bf16 v[32:35], v[156:159], v[164:167], v[32:35]
	ds_read_b128 v[152:155], v204 offset:10240
	v_mfma_f32_16x16x32_bf16 v[36:39], v[156:159], v[168:171], v[36:39]
	ds_read_b128 v[196:199], v221 offset:36864
	v_mfma_f32_16x16x32_bf16 v[40:43], v[156:159], v[172:175], v[40:43]
	s_add_u32 m0, s15, 0x14000
	v_mfma_f32_16x16x32_bf16 v[44:47], v[156:159], v[176:179], v[44:47]
	global_load_lds_dwordx4 v138, s[10:11]
	s_waitcnt lgkmcnt(5)
	v_mfma_f32_16x16x32_bf16 v[48:51], v[160:163], v[164:167], v[48:51]
	ds_read_b128 v[156:159], v204 offset:12288
	v_mfma_f32_16x16x32_bf16 v[52:55], v[160:163], v[168:171], v[52:55]
	ds_read_b128 v[200:203], v221 offset:38912
	v_mfma_f32_16x16x32_bf16 v[56:59], v[160:163], v[172:175], v[56:59]
	s_add_u32 m0, s15, 0x1c000
	v_mfma_f32_16x16x32_bf16 v[60:63], v[160:163], v[176:179], v[60:63]
	global_load_lds_dwordx4 v140, s[24:25]
	s_waitcnt lgkmcnt(5)
	v_mfma_f32_16x16x32_bf16 v[64:67], v[148:151], v[164:167], v[64:67]
	ds_read_b128 v[160:163], v204 offset:14336
	v_mfma_f32_16x16x32_bf16 v[68:71], v[148:151], v[168:171], v[68:71]
	v_mfma_f32_16x16x32_bf16 v[72:75], v[148:151], v[172:175], v[72:75]
	s_add_u32 m0, s15, 0x16000
	v_mfma_f32_16x16x32_bf16 v[76:79], v[148:151], v[176:179], v[76:79]
	global_load_lds_dwordx4 v142, s[10:11]
	s_waitcnt lgkmcnt(4)
	v_mfma_f32_16x16x32_bf16 v[80:83], v[152:155], v[164:167], v[80:83]
	ds_read_b128 v[148:151], v205
	v_mfma_f32_16x16x32_bf16 v[84:87], v[152:155], v[168:171], v[84:87]
	v_mfma_f32_16x16x32_bf16 v[88:91], v[152:155], v[172:175], v[88:91]
	s_add_u32 m0, s15, 0x1e000
	v_mfma_f32_16x16x32_bf16 v[92:95], v[152:155], v[176:179], v[92:95]
	global_load_lds_dwordx4 v144, s[24:25]
	s_add_u32 s10, s10, 0x80
	s_addc_u32 s11, s11, 0
	s_add_u32 s24, s24, 0x80
	s_addc_u32 s25, s25, 0
	s_waitcnt lgkmcnt(3)
	v_mfma_f32_16x16x32_bf16 v[96:99], v[156:159], v[164:167], v[96:99]
	ds_read_b128 v[152:155], v205 offset:2048
	v_mfma_f32_16x16x32_bf16 v[100:103], v[156:159], v[168:171], v[100:103]
	v_mfma_f32_16x16x32_bf16 v[104:107], v[156:159], v[172:175], v[104:107]
	v_mfma_f32_16x16x32_bf16 v[108:111], v[156:159], v[176:179], v[108:111]
	s_waitcnt lgkmcnt(2)
	v_mfma_f32_16x16x32_bf16 v[112:115], v[160:163], v[164:167], v[112:115]
	ds_read_b128 v[156:159], v205 offset:4096
	v_mfma_f32_16x16x32_bf16 v[116:119], v[160:163], v[168:171], v[116:119]
	v_mfma_f32_16x16x32_bf16 v[120:123], v[160:163], v[172:175], v[120:123]
	v_mfma_f32_16x16x32_bf16 v[124:127], v[160:163], v[176:179], v[124:127]
	s_waitcnt lgkmcnt(2)
	v_mfma_f32_16x16x32_bf16 v[0:3], v[148:151], v[180:183], v[0:3]
	ds_read_b128 v[160:163], v205 offset:6144
	v_mfma_f32_16x16x32_bf16 v[4:7], v[148:151], v[184:187], v[4:7]
	v_mfma_f32_16x16x32_bf16 v[8:11], v[148:151], v[196:199], v[8:11]
	v_mfma_f32_16x16x32_bf16 v[12:15], v[148:151], v[200:203], v[12:15]
	s_waitcnt lgkmcnt(2)
	v_mfma_f32_16x16x32_bf16 v[16:19], v[152:155], v[180:183], v[16:19]
	ds_read_b128 v[148:151], v205 offset:8192
	v_mfma_f32_16x16x32_bf16 v[20:23], v[152:155], v[184:187], v[20:23]
	v_mfma_f32_16x16x32_bf16 v[24:27], v[152:155], v[196:199], v[24:27]
	v_mfma_f32_16x16x32_bf16 v[28:31], v[152:155], v[200:203], v[28:31]
	s_waitcnt lgkmcnt(2)
	v_mfma_f32_16x16x32_bf16 v[32:35], v[156:159], v[180:183], v[32:35]
	ds_read_b128 v[152:155], v205 offset:10240
	v_mfma_f32_16x16x32_bf16 v[36:39], v[156:159], v[184:187], v[36:39]
	v_mfma_f32_16x16x32_bf16 v[40:43], v[156:159], v[196:199], v[40:43]
	v_mfma_f32_16x16x32_bf16 v[44:47], v[156:159], v[200:203], v[44:47]
	s_waitcnt lgkmcnt(2)
	v_mfma_f32_16x16x32_bf16 v[48:51], v[160:163], v[180:183], v[48:51]
	ds_read_b128 v[156:159], v205 offset:12288
	v_mfma_f32_16x16x32_bf16 v[52:55], v[160:163], v[184:187], v[52:55]
	v_mfma_f32_16x16x32_bf16 v[56:59], v[160:163], v[196:199], v[56:59]
	v_mfma_f32_16x16x32_bf16 v[60:63], v[160:163], v[200:203], v[60:63]
	s_waitcnt lgkmcnt(2)
	v_mfma_f32_16x16x32_bf16 v[64:67], v[148:151], v[180:183], v[64:67]
	ds_read_b128 v[160:163], v205 offset:14336
	v_mfma_f32_16x16x32_bf16 v[68:71], v[148:151], v[184:187], v[68:71]
	v_mfma_f32_16x16x32_bf16 v[72:75], v[148:151], v[196:199], v[72:75]
	v_mfma_f32_16x16x32_bf16 v[76:79], v[148:151], v[200:203], v[76:79]
	s_waitcnt lgkmcnt(2)
	v_mfma_f32_16x16x32_bf16 v[80:83], v[152:155], v[180:183], v[80:83]
	v_mfma_f32_16x16x32_bf16 v[84:87], v[152:155], v[184:187], v[84:87]
	v_mfma_f32_16x16x32_bf16 v[88:91], v[152:155], v[196:199], v[88:91]
	v_mfma_f32_16x16x32_bf16 v[92:95], v[152:155], v[200:203], v[92:95]
	s_waitcnt lgkmcnt(0)
	s_waitcnt vmcnt(0)
	s_barrier
	v_xor_b32_e32 v204, 0x10000, v204
	v_xor_b32_e32 v205, 0x10000, v205
	v_xor_b32_e32 v220, 0x10000, v220
	v_xor_b32_e32 v221, 0x10000, v221
	v_mfma_f32_16x16x32_bf16 v[96:99], v[156:159], v[180:183], v[96:99]
	ds_read_b128 v[148:151], v204
	ds_read_b128 v[152:155], v204 offset:2048
	s_mov_b32 m0, s15
	v_mfma_f32_16x16x32_bf16 v[100:103], v[156:159], v[184:187], v[100:103]
	global_load_lds_dwordx4 v132, s[10:11]
	v_mfma_f32_16x16x32_bf16 v[104:107], v[156:159], v[196:199], v[104:107]
	ds_read_b128 v[164:167], v220 offset:32768
	ds_read_b128 v[168:171], v220 offset:34816
	s_add_u32 m0, s15, 0x8000
	v_mfma_f32_16x16x32_bf16 v[108:111], v[156:159], v[200:203], v[108:111]
	global_load_lds_dwordx4 v130, s[24:25]
	v_mfma_f32_16x16x32_bf16 v[112:115], v[160:163], v[180:183], v[112:115]
	ds_read_b128 v[156:159], v204 offset:4096
	s_add_u32 m0, s15, 0x2000
	v_mfma_f32_16x16x32_bf16 v[116:119], v[160:163], v[184:187], v[116:119]
	global_load_lds_dwordx4 v134, s[10:11]
	ds_read_b128 v[172:175], v220 offset:36864
	ds_read_b128 v[176:179], v220 offset:38912
	v_mfma_f32_16x16x32_bf16 v[120:123], v[160:163], v[196:199], v[120:123]
	s_add_u32 m0, s15, 0xa000
	v_mfma_f32_16x16x32_bf16 v[124:127], v[160:163], v[200:203], v[124:127]
	global_load_lds_dwordx4 v136, s[24:25]
	s_waitcnt lgkmcnt(4)
	v_mfma_f32_16x16x32_bf16 v[0:3], v[148:151], v[164:167], v[0:3]
	ds_read_b128 v[160:163], v204 offset:6144
	s_waitcnt lgkmcnt(4)
	v_mfma_f32_16x16x32_bf16 v[4:7], v[148:151], v[168:171], v[4:7]
	ds_read_b128 v[180:183], v221 offset:32768
	s_waitcnt lgkmcnt(3)
	v_mfma_f32_16x16x32_bf16 v[8:11], v[148:151], v[172:175], v[8:11]
	s_waitcnt lgkmcnt(2)
	v_mfma_f32_16x16x32_bf16 v[12:15], v[148:151], v[176:179], v[12:15]
	v_mfma_f32_16x16x32_bf16 v[16:19], v[152:155], v[164:167], v[16:19]
	ds_read_b128 v[148:151], v204 offset:8192
	v_mfma_f32_16x16x32_bf16 v[20:23], v[152:155], v[168:171], v[20:23]
	ds_read_b128 v[184:187], v221 offset:34816
	v_mfma_f32_16x16x32_bf16 v[24:27], v[152:155], v[172:175], v[24:27]
	v_mfma_f32_16x16x32_bf16 v[28:31], v[152:155], v[176:179], v[28:31]
	v_mfma_f32_16x16x32_bf16 v[32:35], v[156:159], v[164:167], v[32:35]
	ds_read_b128 v[152:155], v204 offset:10240
	v_mfma_f32_16x16x32_bf16 v[36:39], v[156:159], v[168:171], v[36:39]
	ds_read_b128 v[196:199], v221 offset:36864
	v_mfma_f32_16x16x32_bf16 v[40:43], v[156:159], v[172:175], v[40:43]
	s_add_u32 m0, s15, 0x4000
	v_mfma_f32_16x16x32_bf16 v[44:47], v[156:159], v[176:179], v[44:47]
	global_load_lds_dwordx4 v138, s[10:11]
	s_waitcnt lgkmcnt(5)
	v_mfma_f32_16x16x32_bf16 v[48:51], v[160:163], v[164:167], v[48:51]
	ds_read_b128 v[156:159], v204 offset:12288
	v_mfma_f32_16x16x32_bf16 v[52:55], v[160:163], v[168:171], v[52:55]
	ds_read_b128 v[200:203], v221 offset:38912
	v_mfma_f32_16x16x32_bf16 v[56:59], v[160:163], v[172:175], v[56:59]
	s_add_u32 m0, s15, 0xc000
	v_mfma_f32_16x16x32_bf16 v[60:63], v[160:163], v[176:179], v[60:63]
	global_load_lds_dwordx4 v140, s[24:25]
	s_waitcnt lgkmcnt(5)
	v_mfma_f32_16x16x32_bf16 v[64:67], v[148:151], v[164:167], v[64:67]
	ds_read_b128 v[160:163], v204 offset:14336
	v_mfma_f32_16x16x32_bf16 v[68:71], v[148:151], v[168:171], v[68:71]
	v_mfma_f32_16x16x32_bf16 v[72:75], v[148:151], v[172:175], v[72:75]
	s_add_u32 m0, s15, 0x6000
	v_mfma_f32_16x16x32_bf16 v[76:79], v[148:151], v[176:179], v[76:79]
	global_load_lds_dwordx4 v142, s[10:11]
	s_waitcnt lgkmcnt(4)
	v_mfma_f32_16x16x32_bf16 v[80:83], v[152:155], v[164:167], v[80:83]
	ds_read_b128 v[148:151], v205
	v_mfma_f32_16x16x32_bf16 v[84:87], v[152:155], v[168:171], v[84:87]
	v_mfma_f32_16x16x32_bf16 v[88:91], v[152:155], v[172:175], v[88:91]
	s_add_u32 m0, s15, 0xe000
	v_mfma_f32_16x16x32_bf16 v[92:95], v[152:155], v[176:179], v[92:95]
	global_load_lds_dwordx4 v144, s[24:25]
	s_add_u32 s10, s10, 0x80
	s_addc_u32 s11, s11, 0
	s_add_u32 s24, s24, 0x80
	s_addc_u32 s25, s25, 0
	s_waitcnt lgkmcnt(3)
	v_mfma_f32_16x16x32_bf16 v[96:99], v[156:159], v[164:167], v[96:99]
	ds_read_b128 v[152:155], v205 offset:2048
	v_mfma_f32_16x16x32_bf16 v[100:103], v[156:159], v[168:171], v[100:103]
	v_mfma_f32_16x16x32_bf16 v[104:107], v[156:159], v[172:175], v[104:107]
	v_mfma_f32_16x16x32_bf16 v[108:111], v[156:159], v[176:179], v[108:111]
	s_waitcnt lgkmcnt(2)
	v_mfma_f32_16x16x32_bf16 v[112:115], v[160:163], v[164:167], v[112:115]
	ds_read_b128 v[156:159], v205 offset:4096
	v_mfma_f32_16x16x32_bf16 v[116:119], v[160:163], v[168:171], v[116:119]
	v_mfma_f32_16x16x32_bf16 v[120:123], v[160:163], v[172:175], v[120:123]
	v_mfma_f32_16x16x32_bf16 v[124:127], v[160:163], v[176:179], v[124:127]
	s_waitcnt lgkmcnt(2)
	v_mfma_f32_16x16x32_bf16 v[0:3], v[148:151], v[180:183], v[0:3]
	ds_read_b128 v[160:163], v205 offset:6144
	v_mfma_f32_16x16x32_bf16 v[4:7], v[148:151], v[184:187], v[4:7]
	v_mfma_f32_16x16x32_bf16 v[8:11], v[148:151], v[196:199], v[8:11]
	v_mfma_f32_16x16x32_bf16 v[12:15], v[148:151], v[200:203], v[12:15]
	s_waitcnt lgkmcnt(2)
	v_mfma_f32_16x16x32_bf16 v[16:19], v[152:155], v[180:183], v[16:19]
	ds_read_b128 v[148:151], v205 offset:8192
	v_mfma_f32_16x16x32_bf16 v[20:23], v[152:155], v[184:187], v[20:23]
	v_mfma_f32_16x16x32_bf16 v[24:27], v[152:155], v[196:199], v[24:27]
	v_mfma_f32_16x16x32_bf16 v[28:31], v[152:155], v[200:203], v[28:31]
	s_waitcnt lgkmcnt(2)
	v_mfma_f32_16x16x32_bf16 v[32:35], v[156:159], v[180:183], v[32:35]
	ds_read_b128 v[152:155], v205 offset:10240
	v_mfma_f32_16x16x32_bf16 v[36:39], v[156:159], v[184:187], v[36:39]
	v_mfma_f32_16x16x32_bf16 v[40:43], v[156:159], v[196:199], v[40:43]
	v_mfma_f32_16x16x32_bf16 v[44:47], v[156:159], v[200:203], v[44:47]
	s_waitcnt lgkmcnt(2)
	v_mfma_f32_16x16x32_bf16 v[48:51], v[160:163], v[180:183], v[48:51]
	ds_read_b128 v[156:159], v205 offset:12288
	v_mfma_f32_16x16x32_bf16 v[52:55], v[160:163], v[184:187], v[52:55]
	v_mfma_f32_16x16x32_bf16 v[56:59], v[160:163], v[196:199], v[56:59]
	v_mfma_f32_16x16x32_bf16 v[60:63], v[160:163], v[200:203], v[60:63]
	s_waitcnt lgkmcnt(2)
	v_mfma_f32_16x16x32_bf16 v[64:67], v[148:151], v[180:183], v[64:67]
	ds_read_b128 v[160:163], v205 offset:14336
	v_mfma_f32_16x16x32_bf16 v[68:71], v[148:151], v[184:187], v[68:71]
	v_mfma_f32_16x16x32_bf16 v[72:75], v[148:151], v[196:199], v[72:75]
	v_mfma_f32_16x16x32_bf16 v[76:79], v[148:151], v[200:203], v[76:79]
	s_waitcnt lgkmcnt(2)
	v_mfma_f32_16x16x32_bf16 v[80:83], v[152:155], v[180:183], v[80:83]
	v_mfma_f32_16x16x32_bf16 v[84:87], v[152:155], v[184:187], v[84:87]
	v_mfma_f32_16x16x32_bf16 v[88:91], v[152:155], v[196:199], v[88:91]
	v_mfma_f32_16x16x32_bf16 v[92:95], v[152:155], v[200:203], v[92:95]
	s_waitcnt lgkmcnt(0)
	s_waitcnt vmcnt(0)
	s_barrier
	v_xor_b32_e32 v204, 0x10000, v204
	v_xor_b32_e32 v205, 0x10000, v205
	v_xor_b32_e32 v220, 0x10000, v220
	v_xor_b32_e32 v221, 0x10000, v221
	v_mfma_f32_16x16x32_bf16 v[96:99], v[156:159], v[180:183], v[96:99]
	ds_read_b128 v[148:151], v204
	ds_read_b128 v[152:155], v204 offset:2048
	s_add_u32 m0, s15, 0x10000
	v_mfma_f32_16x16x32_bf16 v[100:103], v[156:159], v[184:187], v[100:103]
	global_load_lds_dwordx4 v132, s[10:11]
	v_mfma_f32_16x16x32_bf16 v[104:107], v[156:159], v[196:199], v[104:107]
	ds_read_b128 v[164:167], v220 offset:32768
	ds_read_b128 v[168:171], v220 offset:34816
	s_add_u32 m0, s15, 0x18000
	v_mfma_f32_16x16x32_bf16 v[108:111], v[156:159], v[200:203], v[108:111]
	global_load_lds_dwordx4 v130, s[24:25]
	v_mfma_f32_16x16x32_bf16 v[112:115], v[160:163], v[180:183], v[112:115]
	ds_read_b128 v[156:159], v204 offset:4096
	s_add_u32 m0, s15, 0x12000
	v_mfma_f32_16x16x32_bf16 v[116:119], v[160:163], v[184:187], v[116:119]
	global_load_lds_dwordx4 v134, s[10:11]
	ds_read_b128 v[172:175], v220 offset:36864
	ds_read_b128 v[176:179], v220 offset:38912
	v_mfma_f32_16x16x32_bf16 v[120:123], v[160:163], v[196:199], v[120:123]
	s_add_u32 m0, s15, 0x1a000
	v_mfma_f32_16x16x32_bf16 v[124:127], v[160:163], v[200:203], v[124:127]
	global_load_lds_dwordx4 v136, s[24:25]
	s_waitcnt lgkmcnt(4)
	v_mfma_f32_16x16x32_bf16 v[0:3], v[148:151], v[164:167], v[0:3]
	ds_read_b128 v[160:163], v204 offset:6144
	s_waitcnt lgkmcnt(4)
	v_mfma_f32_16x16x32_bf16 v[4:7], v[148:151], v[168:171], v[4:7]
	ds_read_b128 v[180:183], v221 offset:32768
	s_waitcnt lgkmcnt(3)
	v_mfma_f32_16x16x32_bf16 v[8:11], v[148:151], v[172:175], v[8:11]
	s_waitcnt lgkmcnt(2)
	v_mfma_f32_16x16x32_bf16 v[12:15], v[148:151], v[176:179], v[12:15]
	v_mfma_f32_16x16x32_bf16 v[16:19], v[152:155], v[164:167], v[16:19]
	ds_read_b128 v[148:151], v204 offset:8192
	v_mfma_f32_16x16x32_bf16 v[20:23], v[152:155], v[168:171], v[20:23]
	ds_read_b128 v[184:187], v221 offset:34816
	v_mfma_f32_16x16x32_bf16 v[24:27], v[152:155], v[172:175], v[24:27]
	v_mfma_f32_16x16x32_bf16 v[28:31], v[152:155], v[176:179], v[28:31]
	v_mfma_f32_16x16x32_bf16 v[32:35], v[156:159], v[164:167], v[32:35]
	ds_read_b128 v[152:155], v204 offset:10240
	v_mfma_f32_16x16x32_bf16 v[36:39], v[156:159], v[168:171], v[36:39]
	ds_read_b128 v[196:199], v221 offset:36864
	v_mfma_f32_16x16x32_bf16 v[40:43], v[156:159], v[172:175], v[40:43]
	s_add_u32 m0, s15, 0x14000
	v_mfma_f32_16x16x32_bf16 v[44:47], v[156:159], v[176:179], v[44:47]
	global_load_lds_dwordx4 v138, s[10:11]
	s_waitcnt lgkmcnt(5)
	v_mfma_f32_16x16x32_bf16 v[48:51], v[160:163], v[164:167], v[48:51]
	ds_read_b128 v[156:159], v204 offset:12288
	v_mfma_f32_16x16x32_bf16 v[52:55], v[160:163], v[168:171], v[52:55]
	ds_read_b128 v[200:203], v221 offset:38912
	v_mfma_f32_16x16x32_bf16 v[56:59], v[160:163], v[172:175], v[56:59]
	s_add_u32 m0, s15, 0x1c000
	v_mfma_f32_16x16x32_bf16 v[60:63], v[160:163], v[176:179], v[60:63]
	global_load_lds_dwordx4 v140, s[24:25]
	s_waitcnt lgkmcnt(5)
	v_mfma_f32_16x16x32_bf16 v[64:67], v[148:151], v[164:167], v[64:67]
	ds_read_b128 v[160:163], v204 offset:14336
	v_mfma_f32_16x16x32_bf16 v[68:71], v[148:151], v[168:171], v[68:71]
	v_mfma_f32_16x16x32_bf16 v[72:75], v[148:151], v[172:175], v[72:75]
	s_add_u32 m0, s15, 0x16000
	v_mfma_f32_16x16x32_bf16 v[76:79], v[148:151], v[176:179], v[76:79]
	global_load_lds_dwordx4 v142, s[10:11]
	s_waitcnt lgkmcnt(4)
	v_mfma_f32_16x16x32_bf16 v[80:83], v[152:155], v[164:167], v[80:83]
	ds_read_b128 v[148:151], v205
	v_mfma_f32_16x16x32_bf16 v[84:87], v[152:155], v[168:171], v[84:87]
	v_mfma_f32_16x16x32_bf16 v[88:91], v[152:155], v[172:175], v[88:91]
	s_add_u32 m0, s15, 0x1e000
	v_mfma_f32_16x16x32_bf16 v[92:95], v[152:155], v[176:179], v[92:95]
	global_load_lds_dwordx4 v144, s[24:25]
	s_add_u32 s10, s10, 0x80
	s_addc_u32 s11, s11, 0
	s_add_u32 s24, s24, 0x80
	s_addc_u32 s25, s25, 0
	s_waitcnt lgkmcnt(3)
	v_mfma_f32_16x16x32_bf16 v[96:99], v[156:159], v[164:167], v[96:99]
	ds_read_b128 v[152:155], v205 offset:2048
	v_mfma_f32_16x16x32_bf16 v[100:103], v[156:159], v[168:171], v[100:103]
	v_mfma_f32_16x16x32_bf16 v[104:107], v[156:159], v[172:175], v[104:107]
	v_mfma_f32_16x16x32_bf16 v[108:111], v[156:159], v[176:179], v[108:111]
	s_waitcnt lgkmcnt(2)
	v_mfma_f32_16x16x32_bf16 v[112:115], v[160:163], v[164:167], v[112:115]
	ds_read_b128 v[156:159], v205 offset:4096
	v_mfma_f32_16x16x32_bf16 v[116:119], v[160:163], v[168:171], v[116:119]
	v_mfma_f32_16x16x32_bf16 v[120:123], v[160:163], v[172:175], v[120:123]
	v_mfma_f32_16x16x32_bf16 v[124:127], v[160:163], v[176:179], v[124:127]
	s_waitcnt lgkmcnt(2)
	v_mfma_f32_16x16x32_bf16 v[0:3], v[148:151], v[180:183], v[0:3]
	ds_read_b128 v[160:163], v205 offset:6144
	v_mfma_f32_16x16x32_bf16 v[4:7], v[148:151], v[184:187], v[4:7]
	v_mfma_f32_16x16x32_bf16 v[8:11], v[148:151], v[196:199], v[8:11]
	v_mfma_f32_16x16x32_bf16 v[12:15], v[148:151], v[200:203], v[12:15]
	s_waitcnt lgkmcnt(2)
	v_mfma_f32_16x16x32_bf16 v[16:19], v[152:155], v[180:183], v[16:19]
	ds_read_b128 v[148:151], v205 offset:8192
	v_mfma_f32_16x16x32_bf16 v[20:23], v[152:155], v[184:187], v[20:23]
	v_mfma_f32_16x16x32_bf16 v[24:27], v[152:155], v[196:199], v[24:27]
	v_mfma_f32_16x16x32_bf16 v[28:31], v[152:155], v[200:203], v[28:31]
	s_waitcnt lgkmcnt(2)
	v_mfma_f32_16x16x32_bf16 v[32:35], v[156:159], v[180:183], v[32:35]
	ds_read_b128 v[152:155], v205 offset:10240
	v_mfma_f32_16x16x32_bf16 v[36:39], v[156:159], v[184:187], v[36:39]
	v_mfma_f32_16x16x32_bf16 v[40:43], v[156:159], v[196:199], v[40:43]
	v_mfma_f32_16x16x32_bf16 v[44:47], v[156:159], v[200:203], v[44:47]
	s_waitcnt lgkmcnt(2)
	v_mfma_f32_16x16x32_bf16 v[48:51], v[160:163], v[180:183], v[48:51]
	ds_read_b128 v[156:159], v205 offset:12288
	v_mfma_f32_16x16x32_bf16 v[52:55], v[160:163], v[184:187], v[52:55]
	v_mfma_f32_16x16x32_bf16 v[56:59], v[160:163], v[196:199], v[56:59]
	v_mfma_f32_16x16x32_bf16 v[60:63], v[160:163], v[200:203], v[60:63]
	s_waitcnt lgkmcnt(2)
	v_mfma_f32_16x16x32_bf16 v[64:67], v[148:151], v[180:183], v[64:67]
	ds_read_b128 v[160:163], v205 offset:14336
	v_mfma_f32_16x16x32_bf16 v[68:71], v[148:151], v[184:187], v[68:71]
	v_mfma_f32_16x16x32_bf16 v[72:75], v[148:151], v[196:199], v[72:75]
	v_mfma_f32_16x16x32_bf16 v[76:79], v[148:151], v[200:203], v[76:79]
	s_waitcnt lgkmcnt(2)
	v_mfma_f32_16x16x32_bf16 v[80:83], v[152:155], v[180:183], v[80:83]
	v_mfma_f32_16x16x32_bf16 v[84:87], v[152:155], v[184:187], v[84:87]
	v_mfma_f32_16x16x32_bf16 v[88:91], v[152:155], v[196:199], v[88:91]
	v_mfma_f32_16x16x32_bf16 v[92:95], v[152:155], v[200:203], v[92:95]
	s_waitcnt lgkmcnt(0)
	s_waitcnt vmcnt(0)
	s_barrier
	v_xor_b32_e32 v204, 0x10000, v204
	v_xor_b32_e32 v205, 0x10000, v205
	v_xor_b32_e32 v220, 0x10000, v220
	v_xor_b32_e32 v221, 0x10000, v221
	v_mfma_f32_16x16x32_bf16 v[96:99], v[156:159], v[180:183], v[96:99]
	ds_read_b128 v[148:151], v204
	ds_read_b128 v[152:155], v204 offset:2048
	s_mov_b32 m0, s15
	v_mfma_f32_16x16x32_bf16 v[100:103], v[156:159], v[184:187], v[100:103]
	global_load_lds_dwordx4 v132, s[10:11]
	v_mfma_f32_16x16x32_bf16 v[104:107], v[156:159], v[196:199], v[104:107]
	ds_read_b128 v[164:167], v220 offset:32768
	ds_read_b128 v[168:171], v220 offset:34816
	s_add_u32 m0, s15, 0x8000
	v_mfma_f32_16x16x32_bf16 v[108:111], v[156:159], v[200:203], v[108:111]
	global_load_lds_dwordx4 v130, s[24:25]
	v_mfma_f32_16x16x32_bf16 v[112:115], v[160:163], v[180:183], v[112:115]
	ds_read_b128 v[156:159], v204 offset:4096
	s_add_u32 m0, s15, 0x2000
	v_mfma_f32_16x16x32_bf16 v[116:119], v[160:163], v[184:187], v[116:119]
	global_load_lds_dwordx4 v134, s[10:11]
	ds_read_b128 v[172:175], v220 offset:36864
	ds_read_b128 v[176:179], v220 offset:38912
	v_mfma_f32_16x16x32_bf16 v[120:123], v[160:163], v[196:199], v[120:123]
	s_add_u32 m0, s15, 0xa000
	v_mfma_f32_16x16x32_bf16 v[124:127], v[160:163], v[200:203], v[124:127]
	global_load_lds_dwordx4 v136, s[24:25]
	s_waitcnt lgkmcnt(4)
	v_mfma_f32_16x16x32_bf16 v[0:3], v[148:151], v[164:167], v[0:3]
	ds_read_b128 v[160:163], v204 offset:6144
	s_waitcnt lgkmcnt(4)
	v_mfma_f32_16x16x32_bf16 v[4:7], v[148:151], v[168:171], v[4:7]
	ds_read_b128 v[180:183], v221 offset:32768
	s_waitcnt lgkmcnt(3)
	v_mfma_f32_16x16x32_bf16 v[8:11], v[148:151], v[172:175], v[8:11]
	s_waitcnt lgkmcnt(2)
	v_mfma_f32_16x16x32_bf16 v[12:15], v[148:151], v[176:179], v[12:15]
	v_mfma_f32_16x16x32_bf16 v[16:19], v[152:155], v[164:167], v[16:19]
	ds_read_b128 v[148:151], v204 offset:8192
	v_mfma_f32_16x16x32_bf16 v[20:23], v[152:155], v[168:171], v[20:23]
	ds_read_b128 v[184:187], v221 offset:34816
	v_mfma_f32_16x16x32_bf16 v[24:27], v[152:155], v[172:175], v[24:27]
	v_mfma_f32_16x16x32_bf16 v[28:31], v[152:155], v[176:179], v[28:31]
	v_mfma_f32_16x16x32_bf16 v[32:35], v[156:159], v[164:167], v[32:35]
	ds_read_b128 v[152:155], v204 offset:10240
	v_mfma_f32_16x16x32_bf16 v[36:39], v[156:159], v[168:171], v[36:39]
	ds_read_b128 v[196:199], v221 offset:36864
	v_mfma_f32_16x16x32_bf16 v[40:43], v[156:159], v[172:175], v[40:43]
	s_add_u32 m0, s15, 0x4000
	v_mfma_f32_16x16x32_bf16 v[44:47], v[156:159], v[176:179], v[44:47]
	global_load_lds_dwordx4 v138, s[10:11]
	s_waitcnt lgkmcnt(5)
	v_mfma_f32_16x16x32_bf16 v[48:51], v[160:163], v[164:167], v[48:51]
	ds_read_b128 v[156:159], v204 offset:12288
	v_mfma_f32_16x16x32_bf16 v[52:55], v[160:163], v[168:171], v[52:55]
	ds_read_b128 v[200:203], v221 offset:38912
	v_mfma_f32_16x16x32_bf16 v[56:59], v[160:163], v[172:175], v[56:59]
	s_add_u32 m0, s15, 0xc000
	v_mfma_f32_16x16x32_bf16 v[60:63], v[160:163], v[176:179], v[60:63]
	global_load_lds_dwordx4 v140, s[24:25]
	s_waitcnt lgkmcnt(5)
	v_mfma_f32_16x16x32_bf16 v[64:67], v[148:151], v[164:167], v[64:67]
	ds_read_b128 v[160:163], v204 offset:14336
	v_mfma_f32_16x16x32_bf16 v[68:71], v[148:151], v[168:171], v[68:71]
	v_mfma_f32_16x16x32_bf16 v[72:75], v[148:151], v[172:175], v[72:75]
	s_add_u32 m0, s15, 0x6000
	v_mfma_f32_16x16x32_bf16 v[76:79], v[148:151], v[176:179], v[76:79]
	global_load_lds_dwordx4 v142, s[10:11]
	s_waitcnt lgkmcnt(4)
	v_mfma_f32_16x16x32_bf16 v[80:83], v[152:155], v[164:167], v[80:83]
	ds_read_b128 v[148:151], v205
	v_mfma_f32_16x16x32_bf16 v[84:87], v[152:155], v[168:171], v[84:87]
	v_mfma_f32_16x16x32_bf16 v[88:91], v[152:155], v[172:175], v[88:91]
	s_add_u32 m0, s15, 0xe000
	v_mfma_f32_16x16x32_bf16 v[92:95], v[152:155], v[176:179], v[92:95]
	global_load_lds_dwordx4 v144, s[24:25]
	s_add_u32 s10, s10, 0x80
	s_addc_u32 s11, s11, 0
	s_add_u32 s24, s24, 0x80
	s_addc_u32 s25, s25, 0
	s_waitcnt lgkmcnt(3)
	v_mfma_f32_16x16x32_bf16 v[96:99], v[156:159], v[164:167], v[96:99]
	ds_read_b128 v[152:155], v205 offset:2048
	v_mfma_f32_16x16x32_bf16 v[100:103], v[156:159], v[168:171], v[100:103]
	v_mfma_f32_16x16x32_bf16 v[104:107], v[156:159], v[172:175], v[104:107]
	v_mfma_f32_16x16x32_bf16 v[108:111], v[156:159], v[176:179], v[108:111]
	s_waitcnt lgkmcnt(2)
	v_mfma_f32_16x16x32_bf16 v[112:115], v[160:163], v[164:167], v[112:115]
	ds_read_b128 v[156:159], v205 offset:4096
	v_mfma_f32_16x16x32_bf16 v[116:119], v[160:163], v[168:171], v[116:119]
	v_mfma_f32_16x16x32_bf16 v[120:123], v[160:163], v[172:175], v[120:123]
	v_mfma_f32_16x16x32_bf16 v[124:127], v[160:163], v[176:179], v[124:127]
	s_waitcnt lgkmcnt(2)
	v_mfma_f32_16x16x32_bf16 v[0:3], v[148:151], v[180:183], v[0:3]
	ds_read_b128 v[160:163], v205 offset:6144
	v_mfma_f32_16x16x32_bf16 v[4:7], v[148:151], v[184:187], v[4:7]
	v_mfma_f32_16x16x32_bf16 v[8:11], v[148:151], v[196:199], v[8:11]
	v_mfma_f32_16x16x32_bf16 v[12:15], v[148:151], v[200:203], v[12:15]
	s_waitcnt lgkmcnt(2)
	v_mfma_f32_16x16x32_bf16 v[16:19], v[152:155], v[180:183], v[16:19]
	ds_read_b128 v[148:151], v205 offset:8192
	v_mfma_f32_16x16x32_bf16 v[20:23], v[152:155], v[184:187], v[20:23]
	v_mfma_f32_16x16x32_bf16 v[24:27], v[152:155], v[196:199], v[24:27]
	v_mfma_f32_16x16x32_bf16 v[28:31], v[152:155], v[200:203], v[28:31]
	s_waitcnt lgkmcnt(2)
	v_mfma_f32_16x16x32_bf16 v[32:35], v[156:159], v[180:183], v[32:35]
	ds_read_b128 v[152:155], v205 offset:10240
	v_mfma_f32_16x16x32_bf16 v[36:39], v[156:159], v[184:187], v[36:39]
	v_mfma_f32_16x16x32_bf16 v[40:43], v[156:159], v[196:199], v[40:43]
	v_mfma_f32_16x16x32_bf16 v[44:47], v[156:159], v[200:203], v[44:47]
	s_waitcnt lgkmcnt(2)
	v_mfma_f32_16x16x32_bf16 v[48:51], v[160:163], v[180:183], v[48:51]
	ds_read_b128 v[156:159], v205 offset:12288
	v_mfma_f32_16x16x32_bf16 v[52:55], v[160:163], v[184:187], v[52:55]
	v_mfma_f32_16x16x32_bf16 v[56:59], v[160:163], v[196:199], v[56:59]
	v_mfma_f32_16x16x32_bf16 v[60:63], v[160:163], v[200:203], v[60:63]
	s_waitcnt lgkmcnt(2)
	v_mfma_f32_16x16x32_bf16 v[64:67], v[148:151], v[180:183], v[64:67]
	ds_read_b128 v[160:163], v205 offset:14336
	v_mfma_f32_16x16x32_bf16 v[68:71], v[148:151], v[184:187], v[68:71]
	v_mfma_f32_16x16x32_bf16 v[72:75], v[148:151], v[196:199], v[72:75]
	v_mfma_f32_16x16x32_bf16 v[76:79], v[148:151], v[200:203], v[76:79]
	s_waitcnt lgkmcnt(2)
	v_mfma_f32_16x16x32_bf16 v[80:83], v[152:155], v[180:183], v[80:83]
	v_mfma_f32_16x16x32_bf16 v[84:87], v[152:155], v[184:187], v[84:87]
	v_mfma_f32_16x16x32_bf16 v[88:91], v[152:155], v[196:199], v[88:91]
	v_mfma_f32_16x16x32_bf16 v[92:95], v[152:155], v[200:203], v[92:95]
	s_waitcnt lgkmcnt(0)
	s_waitcnt vmcnt(0)
	s_barrier
	v_xor_b32_e32 v204, 0x10000, v204
	v_xor_b32_e32 v205, 0x10000, v205
	v_xor_b32_e32 v220, 0x10000, v220
	v_xor_b32_e32 v221, 0x10000, v221
	v_mfma_f32_16x16x32_bf16 v[96:99], v[156:159], v[180:183], v[96:99]
	ds_read_b128 v[148:151], v204
	ds_read_b128 v[152:155], v204 offset:2048
	s_add_u32 m0, s15, 0x10000
	v_mfma_f32_16x16x32_bf16 v[100:103], v[156:159], v[184:187], v[100:103]
	global_load_lds_dwordx4 v132, s[10:11]
	v_mfma_f32_16x16x32_bf16 v[104:107], v[156:159], v[196:199], v[104:107]
	ds_read_b128 v[164:167], v220 offset:32768
	ds_read_b128 v[168:171], v220 offset:34816
	s_add_u32 m0, s15, 0x18000
	v_mfma_f32_16x16x32_bf16 v[108:111], v[156:159], v[200:203], v[108:111]
	global_load_lds_dwordx4 v130, s[24:25]
	v_mfma_f32_16x16x32_bf16 v[112:115], v[160:163], v[180:183], v[112:115]
	ds_read_b128 v[156:159], v204 offset:4096
	s_add_u32 m0, s15, 0x12000
	v_mfma_f32_16x16x32_bf16 v[116:119], v[160:163], v[184:187], v[116:119]
	global_load_lds_dwordx4 v134, s[10:11]
	ds_read_b128 v[172:175], v220 offset:36864
	ds_read_b128 v[176:179], v220 offset:38912
	v_mfma_f32_16x16x32_bf16 v[120:123], v[160:163], v[196:199], v[120:123]
	s_add_u32 m0, s15, 0x1a000
	v_mfma_f32_16x16x32_bf16 v[124:127], v[160:163], v[200:203], v[124:127]
	global_load_lds_dwordx4 v136, s[24:25]
	s_waitcnt lgkmcnt(4)
	v_mfma_f32_16x16x32_bf16 v[0:3], v[148:151], v[164:167], v[0:3]
	ds_read_b128 v[160:163], v204 offset:6144
	s_waitcnt lgkmcnt(4)
	v_mfma_f32_16x16x32_bf16 v[4:7], v[148:151], v[168:171], v[4:7]
	ds_read_b128 v[180:183], v221 offset:32768
	s_waitcnt lgkmcnt(3)
	v_mfma_f32_16x16x32_bf16 v[8:11], v[148:151], v[172:175], v[8:11]
	s_waitcnt lgkmcnt(2)
	v_mfma_f32_16x16x32_bf16 v[12:15], v[148:151], v[176:179], v[12:15]
	v_mfma_f32_16x16x32_bf16 v[16:19], v[152:155], v[164:167], v[16:19]
	ds_read_b128 v[148:151], v204 offset:8192
	v_mfma_f32_16x16x32_bf16 v[20:23], v[152:155], v[168:171], v[20:23]
	ds_read_b128 v[184:187], v221 offset:34816
	v_mfma_f32_16x16x32_bf16 v[24:27], v[152:155], v[172:175], v[24:27]
	v_mfma_f32_16x16x32_bf16 v[28:31], v[152:155], v[176:179], v[28:31]
	v_mfma_f32_16x16x32_bf16 v[32:35], v[156:159], v[164:167], v[32:35]
	ds_read_b128 v[152:155], v204 offset:10240
	v_mfma_f32_16x16x32_bf16 v[36:39], v[156:159], v[168:171], v[36:39]
	ds_read_b128 v[196:199], v221 offset:36864
	v_mfma_f32_16x16x32_bf16 v[40:43], v[156:159], v[172:175], v[40:43]
	s_add_u32 m0, s15, 0x14000
	v_mfma_f32_16x16x32_bf16 v[44:47], v[156:159], v[176:179], v[44:47]
	global_load_lds_dwordx4 v138, s[10:11]
	s_waitcnt lgkmcnt(5)
	v_mfma_f32_16x16x32_bf16 v[48:51], v[160:163], v[164:167], v[48:51]
	ds_read_b128 v[156:159], v204 offset:12288
	v_mfma_f32_16x16x32_bf16 v[52:55], v[160:163], v[168:171], v[52:55]
	ds_read_b128 v[200:203], v221 offset:38912
	v_mfma_f32_16x16x32_bf16 v[56:59], v[160:163], v[172:175], v[56:59]
	s_add_u32 m0, s15, 0x1c000
	v_mfma_f32_16x16x32_bf16 v[60:63], v[160:163], v[176:179], v[60:63]
	global_load_lds_dwordx4 v140, s[24:25]
	s_waitcnt lgkmcnt(5)
	v_mfma_f32_16x16x32_bf16 v[64:67], v[148:151], v[164:167], v[64:67]
	ds_read_b128 v[160:163], v204 offset:14336
	v_mfma_f32_16x16x32_bf16 v[68:71], v[148:151], v[168:171], v[68:71]
	v_mfma_f32_16x16x32_bf16 v[72:75], v[148:151], v[172:175], v[72:75]
	s_add_u32 m0, s15, 0x16000
	v_mfma_f32_16x16x32_bf16 v[76:79], v[148:151], v[176:179], v[76:79]
	global_load_lds_dwordx4 v142, s[10:11]
	s_waitcnt lgkmcnt(4)
	v_mfma_f32_16x16x32_bf16 v[80:83], v[152:155], v[164:167], v[80:83]
	ds_read_b128 v[148:151], v205
	v_mfma_f32_16x16x32_bf16 v[84:87], v[152:155], v[168:171], v[84:87]
	v_mfma_f32_16x16x32_bf16 v[88:91], v[152:155], v[172:175], v[88:91]
	s_add_u32 m0, s15, 0x1e000
	v_mfma_f32_16x16x32_bf16 v[92:95], v[152:155], v[176:179], v[92:95]
	global_load_lds_dwordx4 v144, s[24:25]
	s_add_u32 s10, s10, 0x80
	s_addc_u32 s11, s11, 0
	s_add_u32 s24, s24, 0x80
	s_addc_u32 s25, s25, 0
	s_waitcnt lgkmcnt(3)
	v_mfma_f32_16x16x32_bf16 v[96:99], v[156:159], v[164:167], v[96:99]
	ds_read_b128 v[152:155], v205 offset:2048
	v_mfma_f32_16x16x32_bf16 v[100:103], v[156:159], v[168:171], v[100:103]
	v_mfma_f32_16x16x32_bf16 v[104:107], v[156:159], v[172:175], v[104:107]
	v_mfma_f32_16x16x32_bf16 v[108:111], v[156:159], v[176:179], v[108:111]
	s_waitcnt lgkmcnt(2)
	v_mfma_f32_16x16x32_bf16 v[112:115], v[160:163], v[164:167], v[112:115]
	ds_read_b128 v[156:159], v205 offset:4096
	v_mfma_f32_16x16x32_bf16 v[116:119], v[160:163], v[168:171], v[116:119]
	v_mfma_f32_16x16x32_bf16 v[120:123], v[160:163], v[172:175], v[120:123]
	v_mfma_f32_16x16x32_bf16 v[124:127], v[160:163], v[176:179], v[124:127]
	s_waitcnt lgkmcnt(2)
	v_mfma_f32_16x16x32_bf16 v[0:3], v[148:151], v[180:183], v[0:3]
	ds_read_b128 v[160:163], v205 offset:6144
	v_mfma_f32_16x16x32_bf16 v[4:7], v[148:151], v[184:187], v[4:7]
	v_mfma_f32_16x16x32_bf16 v[8:11], v[148:151], v[196:199], v[8:11]
	v_mfma_f32_16x16x32_bf16 v[12:15], v[148:151], v[200:203], v[12:15]
	s_waitcnt lgkmcnt(2)
	v_mfma_f32_16x16x32_bf16 v[16:19], v[152:155], v[180:183], v[16:19]
	ds_read_b128 v[148:151], v205 offset:8192
	v_mfma_f32_16x16x32_bf16 v[20:23], v[152:155], v[184:187], v[20:23]
	v_mfma_f32_16x16x32_bf16 v[24:27], v[152:155], v[196:199], v[24:27]
	v_mfma_f32_16x16x32_bf16 v[28:31], v[152:155], v[200:203], v[28:31]
	s_waitcnt lgkmcnt(2)
	v_mfma_f32_16x16x32_bf16 v[32:35], v[156:159], v[180:183], v[32:35]
	ds_read_b128 v[152:155], v205 offset:10240
	v_mfma_f32_16x16x32_bf16 v[36:39], v[156:159], v[184:187], v[36:39]
	v_mfma_f32_16x16x32_bf16 v[40:43], v[156:159], v[196:199], v[40:43]
	v_mfma_f32_16x16x32_bf16 v[44:47], v[156:159], v[200:203], v[44:47]
	s_waitcnt lgkmcnt(2)
	v_mfma_f32_16x16x32_bf16 v[48:51], v[160:163], v[180:183], v[48:51]
	ds_read_b128 v[156:159], v205 offset:12288
	v_mfma_f32_16x16x32_bf16 v[52:55], v[160:163], v[184:187], v[52:55]
	v_mfma_f32_16x16x32_bf16 v[56:59], v[160:163], v[196:199], v[56:59]
	v_mfma_f32_16x16x32_bf16 v[60:63], v[160:163], v[200:203], v[60:63]
	s_waitcnt lgkmcnt(2)
	v_mfma_f32_16x16x32_bf16 v[64:67], v[148:151], v[180:183], v[64:67]
	ds_read_b128 v[160:163], v205 offset:14336
	v_mfma_f32_16x16x32_bf16 v[68:71], v[148:151], v[184:187], v[68:71]
	v_mfma_f32_16x16x32_bf16 v[72:75], v[148:151], v[196:199], v[72:75]
	v_mfma_f32_16x16x32_bf16 v[76:79], v[148:151], v[200:203], v[76:79]
	s_waitcnt lgkmcnt(2)
	v_mfma_f32_16x16x32_bf16 v[80:83], v[152:155], v[180:183], v[80:83]
	v_mfma_f32_16x16x32_bf16 v[84:87], v[152:155], v[184:187], v[84:87]
	v_mfma_f32_16x16x32_bf16 v[88:91], v[152:155], v[196:199], v[88:91]
	v_mfma_f32_16x16x32_bf16 v[92:95], v[152:155], v[200:203], v[92:95]
	s_waitcnt lgkmcnt(0)
	s_waitcnt vmcnt(0)
	s_barrier
	v_xor_b32_e32 v204, 0x10000, v204
	v_xor_b32_e32 v205, 0x10000, v205
	v_xor_b32_e32 v220, 0x10000, v220
	v_xor_b32_e32 v221, 0x10000, v221
	v_mfma_f32_16x16x32_bf16 v[96:99], v[156:159], v[180:183], v[96:99]
	ds_read_b128 v[148:151], v204
	ds_read_b128 v[152:155], v204 offset:2048
	s_mov_b32 m0, s15
	v_mfma_f32_16x16x32_bf16 v[100:103], v[156:159], v[184:187], v[100:103]
	global_load_lds_dwordx4 v132, s[10:11]
	v_mfma_f32_16x16x32_bf16 v[104:107], v[156:159], v[196:199], v[104:107]
	ds_read_b128 v[164:167], v220 offset:32768
	ds_read_b128 v[168:171], v220 offset:34816
	s_add_u32 m0, s15, 0x8000
	v_mfma_f32_16x16x32_bf16 v[108:111], v[156:159], v[200:203], v[108:111]
	global_load_lds_dwordx4 v130, s[24:25]
	v_mfma_f32_16x16x32_bf16 v[112:115], v[160:163], v[180:183], v[112:115]
	ds_read_b128 v[156:159], v204 offset:4096
	s_add_u32 m0, s15, 0x2000
	v_mfma_f32_16x16x32_bf16 v[116:119], v[160:163], v[184:187], v[116:119]
	global_load_lds_dwordx4 v134, s[10:11]
	ds_read_b128 v[172:175], v220 offset:36864
	ds_read_b128 v[176:179], v220 offset:38912
	v_mfma_f32_16x16x32_bf16 v[120:123], v[160:163], v[196:199], v[120:123]
	s_add_u32 m0, s15, 0xa000
	v_mfma_f32_16x16x32_bf16 v[124:127], v[160:163], v[200:203], v[124:127]
	global_load_lds_dwordx4 v136, s[24:25]
	s_waitcnt lgkmcnt(4)
	v_mfma_f32_16x16x32_bf16 v[0:3], v[148:151], v[164:167], v[0:3]
	ds_read_b128 v[160:163], v204 offset:6144
	s_waitcnt lgkmcnt(4)
	v_mfma_f32_16x16x32_bf16 v[4:7], v[148:151], v[168:171], v[4:7]
	ds_read_b128 v[180:183], v221 offset:32768
	s_waitcnt lgkmcnt(3)
	v_mfma_f32_16x16x32_bf16 v[8:11], v[148:151], v[172:175], v[8:11]
	s_waitcnt lgkmcnt(2)
	v_mfma_f32_16x16x32_bf16 v[12:15], v[148:151], v[176:179], v[12:15]
	v_mfma_f32_16x16x32_bf16 v[16:19], v[152:155], v[164:167], v[16:19]
	ds_read_b128 v[148:151], v204 offset:8192
	v_mfma_f32_16x16x32_bf16 v[20:23], v[152:155], v[168:171], v[20:23]
	ds_read_b128 v[184:187], v221 offset:34816
	v_mfma_f32_16x16x32_bf16 v[24:27], v[152:155], v[172:175], v[24:27]
	v_mfma_f32_16x16x32_bf16 v[28:31], v[152:155], v[176:179], v[28:31]
	v_mfma_f32_16x16x32_bf16 v[32:35], v[156:159], v[164:167], v[32:35]
	ds_read_b128 v[152:155], v204 offset:10240
	v_mfma_f32_16x16x32_bf16 v[36:39], v[156:159], v[168:171], v[36:39]
	ds_read_b128 v[196:199], v221 offset:36864
	v_mfma_f32_16x16x32_bf16 v[40:43], v[156:159], v[172:175], v[40:43]
	s_add_u32 m0, s15, 0x4000
	v_mfma_f32_16x16x32_bf16 v[44:47], v[156:159], v[176:179], v[44:47]
	global_load_lds_dwordx4 v138, s[10:11]
	s_waitcnt lgkmcnt(5)
	v_mfma_f32_16x16x32_bf16 v[48:51], v[160:163], v[164:167], v[48:51]
	ds_read_b128 v[156:159], v204 offset:12288
	v_mfma_f32_16x16x32_bf16 v[52:55], v[160:163], v[168:171], v[52:55]
	ds_read_b128 v[200:203], v221 offset:38912
	v_mfma_f32_16x16x32_bf16 v[56:59], v[160:163], v[172:175], v[56:59]
	s_add_u32 m0, s15, 0xc000
	v_mfma_f32_16x16x32_bf16 v[60:63], v[160:163], v[176:179], v[60:63]
	global_load_lds_dwordx4 v140, s[24:25]
	s_waitcnt lgkmcnt(5)
	v_mfma_f32_16x16x32_bf16 v[64:67], v[148:151], v[164:167], v[64:67]
	ds_read_b128 v[160:163], v204 offset:14336
	v_mfma_f32_16x16x32_bf16 v[68:71], v[148:151], v[168:171], v[68:71]
	v_mfma_f32_16x16x32_bf16 v[72:75], v[148:151], v[172:175], v[72:75]
	s_add_u32 m0, s15, 0x6000
	v_mfma_f32_16x16x32_bf16 v[76:79], v[148:151], v[176:179], v[76:79]
	global_load_lds_dwordx4 v142, s[10:11]
	s_waitcnt lgkmcnt(4)
	v_mfma_f32_16x16x32_bf16 v[80:83], v[152:155], v[164:167], v[80:83]
	ds_read_b128 v[148:151], v205
	v_mfma_f32_16x16x32_bf16 v[84:87], v[152:155], v[168:171], v[84:87]
	v_mfma_f32_16x16x32_bf16 v[88:91], v[152:155], v[172:175], v[88:91]
	s_add_u32 m0, s15, 0xe000
	v_mfma_f32_16x16x32_bf16 v[92:95], v[152:155], v[176:179], v[92:95]
	global_load_lds_dwordx4 v144, s[24:25]
	s_add_u32 s10, s10, 0x80
	s_addc_u32 s11, s11, 0
	s_add_u32 s24, s24, 0x80
	s_addc_u32 s25, s25, 0
	s_waitcnt lgkmcnt(3)
	v_mfma_f32_16x16x32_bf16 v[96:99], v[156:159], v[164:167], v[96:99]
	ds_read_b128 v[152:155], v205 offset:2048
	v_mfma_f32_16x16x32_bf16 v[100:103], v[156:159], v[168:171], v[100:103]
	v_mfma_f32_16x16x32_bf16 v[104:107], v[156:159], v[172:175], v[104:107]
	v_mfma_f32_16x16x32_bf16 v[108:111], v[156:159], v[176:179], v[108:111]
	s_waitcnt lgkmcnt(2)
	v_mfma_f32_16x16x32_bf16 v[112:115], v[160:163], v[164:167], v[112:115]
	ds_read_b128 v[156:159], v205 offset:4096
	v_mfma_f32_16x16x32_bf16 v[116:119], v[160:163], v[168:171], v[116:119]
	v_mfma_f32_16x16x32_bf16 v[120:123], v[160:163], v[172:175], v[120:123]
	v_mfma_f32_16x16x32_bf16 v[124:127], v[160:163], v[176:179], v[124:127]
	s_waitcnt lgkmcnt(2)
	v_mfma_f32_16x16x32_bf16 v[0:3], v[148:151], v[180:183], v[0:3]
	ds_read_b128 v[160:163], v205 offset:6144
	v_mfma_f32_16x16x32_bf16 v[4:7], v[148:151], v[184:187], v[4:7]
	v_mfma_f32_16x16x32_bf16 v[8:11], v[148:151], v[196:199], v[8:11]
	v_mfma_f32_16x16x32_bf16 v[12:15], v[148:151], v[200:203], v[12:15]
	s_waitcnt lgkmcnt(2)
	v_mfma_f32_16x16x32_bf16 v[16:19], v[152:155], v[180:183], v[16:19]
	ds_read_b128 v[148:151], v205 offset:8192
	v_mfma_f32_16x16x32_bf16 v[20:23], v[152:155], v[184:187], v[20:23]
	v_mfma_f32_16x16x32_bf16 v[24:27], v[152:155], v[196:199], v[24:27]
	v_mfma_f32_16x16x32_bf16 v[28:31], v[152:155], v[200:203], v[28:31]
	s_waitcnt lgkmcnt(2)
	v_mfma_f32_16x16x32_bf16 v[32:35], v[156:159], v[180:183], v[32:35]
	ds_read_b128 v[152:155], v205 offset:10240
	v_mfma_f32_16x16x32_bf16 v[36:39], v[156:159], v[184:187], v[36:39]
	v_mfma_f32_16x16x32_bf16 v[40:43], v[156:159], v[196:199], v[40:43]
	v_mfma_f32_16x16x32_bf16 v[44:47], v[156:159], v[200:203], v[44:47]
	s_waitcnt lgkmcnt(2)
	v_mfma_f32_16x16x32_bf16 v[48:51], v[160:163], v[180:183], v[48:51]
	ds_read_b128 v[156:159], v205 offset:12288
	v_mfma_f32_16x16x32_bf16 v[52:55], v[160:163], v[184:187], v[52:55]
	v_mfma_f32_16x16x32_bf16 v[56:59], v[160:163], v[196:199], v[56:59]
	v_mfma_f32_16x16x32_bf16 v[60:63], v[160:163], v[200:203], v[60:63]
	s_waitcnt lgkmcnt(2)
	v_mfma_f32_16x16x32_bf16 v[64:67], v[148:151], v[180:183], v[64:67]
	ds_read_b128 v[160:163], v205 offset:14336
	v_mfma_f32_16x16x32_bf16 v[68:71], v[148:151], v[184:187], v[68:71]
	v_mfma_f32_16x16x32_bf16 v[72:75], v[148:151], v[196:199], v[72:75]
	v_mfma_f32_16x16x32_bf16 v[76:79], v[148:151], v[200:203], v[76:79]
	s_waitcnt lgkmcnt(2)
	v_mfma_f32_16x16x32_bf16 v[80:83], v[152:155], v[180:183], v[80:83]
	v_mfma_f32_16x16x32_bf16 v[84:87], v[152:155], v[184:187], v[84:87]
	v_mfma_f32_16x16x32_bf16 v[88:91], v[152:155], v[196:199], v[88:91]
	v_mfma_f32_16x16x32_bf16 v[92:95], v[152:155], v[200:203], v[92:95]
	s_waitcnt lgkmcnt(0)
	s_waitcnt vmcnt(0)
	s_barrier
	v_xor_b32_e32 v204, 0x10000, v204
	v_xor_b32_e32 v205, 0x10000, v205
	v_xor_b32_e32 v220, 0x10000, v220
	v_xor_b32_e32 v221, 0x10000, v221
	v_mfma_f32_16x16x32_bf16 v[96:99], v[156:159], v[180:183], v[96:99]
	ds_read_b128 v[148:151], v204
	ds_read_b128 v[152:155], v204 offset:2048
	s_add_u32 m0, s15, 0x10000
	v_mfma_f32_16x16x32_bf16 v[100:103], v[156:159], v[184:187], v[100:103]
	global_load_lds_dwordx4 v132, s[10:11]
	v_mfma_f32_16x16x32_bf16 v[104:107], v[156:159], v[196:199], v[104:107]
	ds_read_b128 v[164:167], v220 offset:32768
	ds_read_b128 v[168:171], v220 offset:34816
	s_add_u32 m0, s15, 0x18000
	v_mfma_f32_16x16x32_bf16 v[108:111], v[156:159], v[200:203], v[108:111]
	global_load_lds_dwordx4 v130, s[24:25]
	v_mfma_f32_16x16x32_bf16 v[112:115], v[160:163], v[180:183], v[112:115]
	ds_read_b128 v[156:159], v204 offset:4096
	s_add_u32 m0, s15, 0x12000
	v_mfma_f32_16x16x32_bf16 v[116:119], v[160:163], v[184:187], v[116:119]
	global_load_lds_dwordx4 v134, s[10:11]
	ds_read_b128 v[172:175], v220 offset:36864
	ds_read_b128 v[176:179], v220 offset:38912
	v_mfma_f32_16x16x32_bf16 v[120:123], v[160:163], v[196:199], v[120:123]
	s_add_u32 m0, s15, 0x1a000
	v_mfma_f32_16x16x32_bf16 v[124:127], v[160:163], v[200:203], v[124:127]
	global_load_lds_dwordx4 v136, s[24:25]
	s_waitcnt lgkmcnt(4)
	v_mfma_f32_16x16x32_bf16 v[0:3], v[148:151], v[164:167], v[0:3]
	ds_read_b128 v[160:163], v204 offset:6144
	s_waitcnt lgkmcnt(4)
	v_mfma_f32_16x16x32_bf16 v[4:7], v[148:151], v[168:171], v[4:7]
	ds_read_b128 v[180:183], v221 offset:32768
	s_waitcnt lgkmcnt(3)
	v_mfma_f32_16x16x32_bf16 v[8:11], v[148:151], v[172:175], v[8:11]
	s_waitcnt lgkmcnt(2)
	v_mfma_f32_16x16x32_bf16 v[12:15], v[148:151], v[176:179], v[12:15]
	v_mfma_f32_16x16x32_bf16 v[16:19], v[152:155], v[164:167], v[16:19]
	ds_read_b128 v[148:151], v204 offset:8192
	v_mfma_f32_16x16x32_bf16 v[20:23], v[152:155], v[168:171], v[20:23]
	ds_read_b128 v[184:187], v221 offset:34816
	v_mfma_f32_16x16x32_bf16 v[24:27], v[152:155], v[172:175], v[24:27]
	v_mfma_f32_16x16x32_bf16 v[28:31], v[152:155], v[176:179], v[28:31]
	v_mfma_f32_16x16x32_bf16 v[32:35], v[156:159], v[164:167], v[32:35]
	ds_read_b128 v[152:155], v204 offset:10240
	v_mfma_f32_16x16x32_bf16 v[36:39], v[156:159], v[168:171], v[36:39]
	ds_read_b128 v[196:199], v221 offset:36864
	v_mfma_f32_16x16x32_bf16 v[40:43], v[156:159], v[172:175], v[40:43]
	s_add_u32 m0, s15, 0x14000
	v_mfma_f32_16x16x32_bf16 v[44:47], v[156:159], v[176:179], v[44:47]
	global_load_lds_dwordx4 v138, s[10:11]
	s_waitcnt lgkmcnt(5)
	v_mfma_f32_16x16x32_bf16 v[48:51], v[160:163], v[164:167], v[48:51]
	ds_read_b128 v[156:159], v204 offset:12288
	v_mfma_f32_16x16x32_bf16 v[52:55], v[160:163], v[168:171], v[52:55]
	ds_read_b128 v[200:203], v221 offset:38912
	v_mfma_f32_16x16x32_bf16 v[56:59], v[160:163], v[172:175], v[56:59]
	s_add_u32 m0, s15, 0x1c000
	v_mfma_f32_16x16x32_bf16 v[60:63], v[160:163], v[176:179], v[60:63]
	global_load_lds_dwordx4 v140, s[24:25]
	s_waitcnt lgkmcnt(5)
	v_mfma_f32_16x16x32_bf16 v[64:67], v[148:151], v[164:167], v[64:67]
	ds_read_b128 v[160:163], v204 offset:14336
	v_mfma_f32_16x16x32_bf16 v[68:71], v[148:151], v[168:171], v[68:71]
	v_mfma_f32_16x16x32_bf16 v[72:75], v[148:151], v[172:175], v[72:75]
	s_add_u32 m0, s15, 0x16000
	v_mfma_f32_16x16x32_bf16 v[76:79], v[148:151], v[176:179], v[76:79]
	global_load_lds_dwordx4 v142, s[10:11]
	s_waitcnt lgkmcnt(4)
	v_mfma_f32_16x16x32_bf16 v[80:83], v[152:155], v[164:167], v[80:83]
	ds_read_b128 v[148:151], v205
	v_mfma_f32_16x16x32_bf16 v[84:87], v[152:155], v[168:171], v[84:87]
	v_mfma_f32_16x16x32_bf16 v[88:91], v[152:155], v[172:175], v[88:91]
	s_add_u32 m0, s15, 0x1e000
	v_mfma_f32_16x16x32_bf16 v[92:95], v[152:155], v[176:179], v[92:95]
	global_load_lds_dwordx4 v144, s[24:25]
	s_add_u32 s10, s10, 0x80
	s_addc_u32 s11, s11, 0
	s_add_u32 s24, s24, 0x80
	s_addc_u32 s25, s25, 0
	s_waitcnt lgkmcnt(3)
	v_mfma_f32_16x16x32_bf16 v[96:99], v[156:159], v[164:167], v[96:99]
	ds_read_b128 v[152:155], v205 offset:2048
	v_mfma_f32_16x16x32_bf16 v[100:103], v[156:159], v[168:171], v[100:103]
	v_mfma_f32_16x16x32_bf16 v[104:107], v[156:159], v[172:175], v[104:107]
	v_mfma_f32_16x16x32_bf16 v[108:111], v[156:159], v[176:179], v[108:111]
	s_waitcnt lgkmcnt(2)
	v_mfma_f32_16x16x32_bf16 v[112:115], v[160:163], v[164:167], v[112:115]
	ds_read_b128 v[156:159], v205 offset:4096
	v_mfma_f32_16x16x32_bf16 v[116:119], v[160:163], v[168:171], v[116:119]
	v_mfma_f32_16x16x32_bf16 v[120:123], v[160:163], v[172:175], v[120:123]
	v_mfma_f32_16x16x32_bf16 v[124:127], v[160:163], v[176:179], v[124:127]
	s_waitcnt lgkmcnt(2)
	v_mfma_f32_16x16x32_bf16 v[0:3], v[148:151], v[180:183], v[0:3]
	ds_read_b128 v[160:163], v205 offset:6144
	v_mfma_f32_16x16x32_bf16 v[4:7], v[148:151], v[184:187], v[4:7]
	v_mfma_f32_16x16x32_bf16 v[8:11], v[148:151], v[196:199], v[8:11]
	v_mfma_f32_16x16x32_bf16 v[12:15], v[148:151], v[200:203], v[12:15]
	s_waitcnt lgkmcnt(2)
	v_mfma_f32_16x16x32_bf16 v[16:19], v[152:155], v[180:183], v[16:19]
	ds_read_b128 v[148:151], v205 offset:8192
	v_mfma_f32_16x16x32_bf16 v[20:23], v[152:155], v[184:187], v[20:23]
	v_mfma_f32_16x16x32_bf16 v[24:27], v[152:155], v[196:199], v[24:27]
	v_mfma_f32_16x16x32_bf16 v[28:31], v[152:155], v[200:203], v[28:31]
	s_waitcnt lgkmcnt(2)
	v_mfma_f32_16x16x32_bf16 v[32:35], v[156:159], v[180:183], v[32:35]
	ds_read_b128 v[152:155], v205 offset:10240
	v_mfma_f32_16x16x32_bf16 v[36:39], v[156:159], v[184:187], v[36:39]
	v_mfma_f32_16x16x32_bf16 v[40:43], v[156:159], v[196:199], v[40:43]
	v_mfma_f32_16x16x32_bf16 v[44:47], v[156:159], v[200:203], v[44:47]
	s_waitcnt lgkmcnt(2)
	v_mfma_f32_16x16x32_bf16 v[48:51], v[160:163], v[180:183], v[48:51]
	ds_read_b128 v[156:159], v205 offset:12288
	v_mfma_f32_16x16x32_bf16 v[52:55], v[160:163], v[184:187], v[52:55]
	v_mfma_f32_16x16x32_bf16 v[56:59], v[160:163], v[196:199], v[56:59]
	v_mfma_f32_16x16x32_bf16 v[60:63], v[160:163], v[200:203], v[60:63]
	s_waitcnt lgkmcnt(2)
	v_mfma_f32_16x16x32_bf16 v[64:67], v[148:151], v[180:183], v[64:67]
	ds_read_b128 v[160:163], v205 offset:14336
	v_mfma_f32_16x16x32_bf16 v[68:71], v[148:151], v[184:187], v[68:71]
	v_mfma_f32_16x16x32_bf16 v[72:75], v[148:151], v[196:199], v[72:75]
	v_mfma_f32_16x16x32_bf16 v[76:79], v[148:151], v[200:203], v[76:79]
	s_waitcnt lgkmcnt(2)
	v_mfma_f32_16x16x32_bf16 v[80:83], v[152:155], v[180:183], v[80:83]
	v_mfma_f32_16x16x32_bf16 v[84:87], v[152:155], v[184:187], v[84:87]
	v_mfma_f32_16x16x32_bf16 v[88:91], v[152:155], v[196:199], v[88:91]
	v_mfma_f32_16x16x32_bf16 v[92:95], v[152:155], v[200:203], v[92:95]
	s_waitcnt lgkmcnt(0)
	s_waitcnt vmcnt(0)
	s_barrier
	v_xor_b32_e32 v204, 0x10000, v204
	v_xor_b32_e32 v205, 0x10000, v205
	v_xor_b32_e32 v220, 0x10000, v220
	v_xor_b32_e32 v221, 0x10000, v221
	v_mfma_f32_16x16x32_bf16 v[96:99], v[156:159], v[180:183], v[96:99]
	ds_read_b128 v[148:151], v204
	ds_read_b128 v[152:155], v204 offset:2048
	s_mov_b32 m0, s15
	v_mfma_f32_16x16x32_bf16 v[100:103], v[156:159], v[184:187], v[100:103]
	global_load_lds_dwordx4 v132, s[10:11]
	v_mfma_f32_16x16x32_bf16 v[104:107], v[156:159], v[196:199], v[104:107]
	ds_read_b128 v[164:167], v220 offset:32768
	ds_read_b128 v[168:171], v220 offset:34816
	s_add_u32 m0, s15, 0x8000
	v_mfma_f32_16x16x32_bf16 v[108:111], v[156:159], v[200:203], v[108:111]
	global_load_lds_dwordx4 v130, s[24:25]
	v_mfma_f32_16x16x32_bf16 v[112:115], v[160:163], v[180:183], v[112:115]
	ds_read_b128 v[156:159], v204 offset:4096
	s_add_u32 m0, s15, 0x2000
	v_mfma_f32_16x16x32_bf16 v[116:119], v[160:163], v[184:187], v[116:119]
	global_load_lds_dwordx4 v134, s[10:11]
	ds_read_b128 v[172:175], v220 offset:36864
	ds_read_b128 v[176:179], v220 offset:38912
	v_mfma_f32_16x16x32_bf16 v[120:123], v[160:163], v[196:199], v[120:123]
	s_add_u32 m0, s15, 0xa000
	v_mfma_f32_16x16x32_bf16 v[124:127], v[160:163], v[200:203], v[124:127]
	global_load_lds_dwordx4 v136, s[24:25]
	s_waitcnt lgkmcnt(4)
	v_mfma_f32_16x16x32_bf16 v[0:3], v[148:151], v[164:167], v[0:3]
	ds_read_b128 v[160:163], v204 offset:6144
	s_waitcnt lgkmcnt(4)
	v_mfma_f32_16x16x32_bf16 v[4:7], v[148:151], v[168:171], v[4:7]
	ds_read_b128 v[180:183], v221 offset:32768
	s_waitcnt lgkmcnt(3)
	v_mfma_f32_16x16x32_bf16 v[8:11], v[148:151], v[172:175], v[8:11]
	s_waitcnt lgkmcnt(2)
	v_mfma_f32_16x16x32_bf16 v[12:15], v[148:151], v[176:179], v[12:15]
	v_mfma_f32_16x16x32_bf16 v[16:19], v[152:155], v[164:167], v[16:19]
	ds_read_b128 v[148:151], v204 offset:8192
	v_mfma_f32_16x16x32_bf16 v[20:23], v[152:155], v[168:171], v[20:23]
	ds_read_b128 v[184:187], v221 offset:34816
	v_mfma_f32_16x16x32_bf16 v[24:27], v[152:155], v[172:175], v[24:27]
	v_mfma_f32_16x16x32_bf16 v[28:31], v[152:155], v[176:179], v[28:31]
	v_mfma_f32_16x16x32_bf16 v[32:35], v[156:159], v[164:167], v[32:35]
	ds_read_b128 v[152:155], v204 offset:10240
	v_mfma_f32_16x16x32_bf16 v[36:39], v[156:159], v[168:171], v[36:39]
	ds_read_b128 v[196:199], v221 offset:36864
	v_mfma_f32_16x16x32_bf16 v[40:43], v[156:159], v[172:175], v[40:43]
	s_add_u32 m0, s15, 0x4000
	v_mfma_f32_16x16x32_bf16 v[44:47], v[156:159], v[176:179], v[44:47]
	global_load_lds_dwordx4 v138, s[10:11]
	s_waitcnt lgkmcnt(5)
	v_mfma_f32_16x16x32_bf16 v[48:51], v[160:163], v[164:167], v[48:51]
	ds_read_b128 v[156:159], v204 offset:12288
	v_mfma_f32_16x16x32_bf16 v[52:55], v[160:163], v[168:171], v[52:55]
	ds_read_b128 v[200:203], v221 offset:38912
	v_mfma_f32_16x16x32_bf16 v[56:59], v[160:163], v[172:175], v[56:59]
	s_add_u32 m0, s15, 0xc000
	v_mfma_f32_16x16x32_bf16 v[60:63], v[160:163], v[176:179], v[60:63]
	global_load_lds_dwordx4 v140, s[24:25]
	s_waitcnt lgkmcnt(5)
	v_mfma_f32_16x16x32_bf16 v[64:67], v[148:151], v[164:167], v[64:67]
	ds_read_b128 v[160:163], v204 offset:14336
	v_mfma_f32_16x16x32_bf16 v[68:71], v[148:151], v[168:171], v[68:71]
	v_mfma_f32_16x16x32_bf16 v[72:75], v[148:151], v[172:175], v[72:75]
	s_add_u32 m0, s15, 0x6000
	v_mfma_f32_16x16x32_bf16 v[76:79], v[148:151], v[176:179], v[76:79]
	global_load_lds_dwordx4 v142, s[10:11]
	s_waitcnt lgkmcnt(4)
	v_mfma_f32_16x16x32_bf16 v[80:83], v[152:155], v[164:167], v[80:83]
	ds_read_b128 v[148:151], v205
	v_mfma_f32_16x16x32_bf16 v[84:87], v[152:155], v[168:171], v[84:87]
	v_mfma_f32_16x16x32_bf16 v[88:91], v[152:155], v[172:175], v[88:91]
	s_add_u32 m0, s15, 0xe000
	v_mfma_f32_16x16x32_bf16 v[92:95], v[152:155], v[176:179], v[92:95]
	global_load_lds_dwordx4 v144, s[24:25]
	s_add_u32 s10, s10, 0x80
	s_addc_u32 s11, s11, 0
	s_add_u32 s24, s24, 0x80
	s_addc_u32 s25, s25, 0
	s_waitcnt lgkmcnt(3)
	v_mfma_f32_16x16x32_bf16 v[96:99], v[156:159], v[164:167], v[96:99]
	ds_read_b128 v[152:155], v205 offset:2048
	v_mfma_f32_16x16x32_bf16 v[100:103], v[156:159], v[168:171], v[100:103]
	v_mfma_f32_16x16x32_bf16 v[104:107], v[156:159], v[172:175], v[104:107]
	v_mfma_f32_16x16x32_bf16 v[108:111], v[156:159], v[176:179], v[108:111]
	s_waitcnt lgkmcnt(2)
	v_mfma_f32_16x16x32_bf16 v[112:115], v[160:163], v[164:167], v[112:115]
	ds_read_b128 v[156:159], v205 offset:4096
	v_mfma_f32_16x16x32_bf16 v[116:119], v[160:163], v[168:171], v[116:119]
	v_mfma_f32_16x16x32_bf16 v[120:123], v[160:163], v[172:175], v[120:123]
	v_mfma_f32_16x16x32_bf16 v[124:127], v[160:163], v[176:179], v[124:127]
	s_waitcnt lgkmcnt(2)
	v_mfma_f32_16x16x32_bf16 v[0:3], v[148:151], v[180:183], v[0:3]
	ds_read_b128 v[160:163], v205 offset:6144
	v_mfma_f32_16x16x32_bf16 v[4:7], v[148:151], v[184:187], v[4:7]
	v_mfma_f32_16x16x32_bf16 v[8:11], v[148:151], v[196:199], v[8:11]
	v_mfma_f32_16x16x32_bf16 v[12:15], v[148:151], v[200:203], v[12:15]
	s_waitcnt lgkmcnt(2)
	v_mfma_f32_16x16x32_bf16 v[16:19], v[152:155], v[180:183], v[16:19]
	ds_read_b128 v[148:151], v205 offset:8192
	v_mfma_f32_16x16x32_bf16 v[20:23], v[152:155], v[184:187], v[20:23]
	v_mfma_f32_16x16x32_bf16 v[24:27], v[152:155], v[196:199], v[24:27]
	v_mfma_f32_16x16x32_bf16 v[28:31], v[152:155], v[200:203], v[28:31]
	s_waitcnt lgkmcnt(2)
	v_mfma_f32_16x16x32_bf16 v[32:35], v[156:159], v[180:183], v[32:35]
	ds_read_b128 v[152:155], v205 offset:10240
	v_mfma_f32_16x16x32_bf16 v[36:39], v[156:159], v[184:187], v[36:39]
	v_mfma_f32_16x16x32_bf16 v[40:43], v[156:159], v[196:199], v[40:43]
	v_mfma_f32_16x16x32_bf16 v[44:47], v[156:159], v[200:203], v[44:47]
	s_waitcnt lgkmcnt(2)
	v_mfma_f32_16x16x32_bf16 v[48:51], v[160:163], v[180:183], v[48:51]
	ds_read_b128 v[156:159], v205 offset:12288
	v_mfma_f32_16x16x32_bf16 v[52:55], v[160:163], v[184:187], v[52:55]
	v_mfma_f32_16x16x32_bf16 v[56:59], v[160:163], v[196:199], v[56:59]
	v_mfma_f32_16x16x32_bf16 v[60:63], v[160:163], v[200:203], v[60:63]
	s_waitcnt lgkmcnt(2)
	v_mfma_f32_16x16x32_bf16 v[64:67], v[148:151], v[180:183], v[64:67]
	ds_read_b128 v[160:163], v205 offset:14336
	v_mfma_f32_16x16x32_bf16 v[68:71], v[148:151], v[184:187], v[68:71]
	v_mfma_f32_16x16x32_bf16 v[72:75], v[148:151], v[196:199], v[72:75]
	v_mfma_f32_16x16x32_bf16 v[76:79], v[148:151], v[200:203], v[76:79]
	s_waitcnt lgkmcnt(2)
	v_mfma_f32_16x16x32_bf16 v[80:83], v[152:155], v[180:183], v[80:83]
	v_mfma_f32_16x16x32_bf16 v[84:87], v[152:155], v[184:187], v[84:87]
	v_mfma_f32_16x16x32_bf16 v[88:91], v[152:155], v[196:199], v[88:91]
	v_mfma_f32_16x16x32_bf16 v[92:95], v[152:155], v[200:203], v[92:95]
	s_waitcnt lgkmcnt(0)
	s_waitcnt vmcnt(0)
	s_barrier
	v_xor_b32_e32 v204, 0x10000, v204
	v_xor_b32_e32 v205, 0x10000, v205
	v_xor_b32_e32 v220, 0x10000, v220
	v_xor_b32_e32 v221, 0x10000, v221
	v_mfma_f32_16x16x32_bf16 v[96:99], v[156:159], v[180:183], v[96:99]
	ds_read_b128 v[148:151], v204
	ds_read_b128 v[152:155], v204 offset:2048
	s_add_u32 m0, s15, 0x10000
	v_mfma_f32_16x16x32_bf16 v[100:103], v[156:159], v[184:187], v[100:103]
	global_load_lds_dwordx4 v132, s[10:11]
	v_mfma_f32_16x16x32_bf16 v[104:107], v[156:159], v[196:199], v[104:107]
	ds_read_b128 v[164:167], v220 offset:32768
	ds_read_b128 v[168:171], v220 offset:34816
	s_add_u32 m0, s15, 0x18000
	v_mfma_f32_16x16x32_bf16 v[108:111], v[156:159], v[200:203], v[108:111]
	global_load_lds_dwordx4 v130, s[24:25]
	v_mfma_f32_16x16x32_bf16 v[112:115], v[160:163], v[180:183], v[112:115]
	ds_read_b128 v[156:159], v204 offset:4096
	s_add_u32 m0, s15, 0x12000
	v_mfma_f32_16x16x32_bf16 v[116:119], v[160:163], v[184:187], v[116:119]
	global_load_lds_dwordx4 v134, s[10:11]
	ds_read_b128 v[172:175], v220 offset:36864
	ds_read_b128 v[176:179], v220 offset:38912
	v_mfma_f32_16x16x32_bf16 v[120:123], v[160:163], v[196:199], v[120:123]
	s_add_u32 m0, s15, 0x1a000
	v_mfma_f32_16x16x32_bf16 v[124:127], v[160:163], v[200:203], v[124:127]
	global_load_lds_dwordx4 v136, s[24:25]
	s_waitcnt lgkmcnt(4)
	v_mfma_f32_16x16x32_bf16 v[0:3], v[148:151], v[164:167], v[0:3]
	ds_read_b128 v[160:163], v204 offset:6144
	s_waitcnt lgkmcnt(4)
	v_mfma_f32_16x16x32_bf16 v[4:7], v[148:151], v[168:171], v[4:7]
	ds_read_b128 v[180:183], v221 offset:32768
	s_waitcnt lgkmcnt(3)
	v_mfma_f32_16x16x32_bf16 v[8:11], v[148:151], v[172:175], v[8:11]
	s_waitcnt lgkmcnt(2)
	v_mfma_f32_16x16x32_bf16 v[12:15], v[148:151], v[176:179], v[12:15]
	v_mfma_f32_16x16x32_bf16 v[16:19], v[152:155], v[164:167], v[16:19]
	ds_read_b128 v[148:151], v204 offset:8192
	v_mfma_f32_16x16x32_bf16 v[20:23], v[152:155], v[168:171], v[20:23]
	ds_read_b128 v[184:187], v221 offset:34816
	v_mfma_f32_16x16x32_bf16 v[24:27], v[152:155], v[172:175], v[24:27]
	v_mfma_f32_16x16x32_bf16 v[28:31], v[152:155], v[176:179], v[28:31]
	v_mfma_f32_16x16x32_bf16 v[32:35], v[156:159], v[164:167], v[32:35]
	ds_read_b128 v[152:155], v204 offset:10240
	v_mfma_f32_16x16x32_bf16 v[36:39], v[156:159], v[168:171], v[36:39]
	ds_read_b128 v[196:199], v221 offset:36864
	v_mfma_f32_16x16x32_bf16 v[40:43], v[156:159], v[172:175], v[40:43]
	s_add_u32 m0, s15, 0x14000
	v_mfma_f32_16x16x32_bf16 v[44:47], v[156:159], v[176:179], v[44:47]
	global_load_lds_dwordx4 v138, s[10:11]
	s_waitcnt lgkmcnt(5)
	v_mfma_f32_16x16x32_bf16 v[48:51], v[160:163], v[164:167], v[48:51]
	ds_read_b128 v[156:159], v204 offset:12288
	v_mfma_f32_16x16x32_bf16 v[52:55], v[160:163], v[168:171], v[52:55]
	ds_read_b128 v[200:203], v221 offset:38912
	v_mfma_f32_16x16x32_bf16 v[56:59], v[160:163], v[172:175], v[56:59]
	s_add_u32 m0, s15, 0x1c000
	v_mfma_f32_16x16x32_bf16 v[60:63], v[160:163], v[176:179], v[60:63]
	global_load_lds_dwordx4 v140, s[24:25]
	s_waitcnt lgkmcnt(5)
	v_mfma_f32_16x16x32_bf16 v[64:67], v[148:151], v[164:167], v[64:67]
	ds_read_b128 v[160:163], v204 offset:14336
	v_mfma_f32_16x16x32_bf16 v[68:71], v[148:151], v[168:171], v[68:71]
	v_mfma_f32_16x16x32_bf16 v[72:75], v[148:151], v[172:175], v[72:75]
	s_add_u32 m0, s15, 0x16000
	v_mfma_f32_16x16x32_bf16 v[76:79], v[148:151], v[176:179], v[76:79]
	global_load_lds_dwordx4 v142, s[10:11]
	s_waitcnt lgkmcnt(4)
	v_mfma_f32_16x16x32_bf16 v[80:83], v[152:155], v[164:167], v[80:83]
	ds_read_b128 v[148:151], v205
	v_mfma_f32_16x16x32_bf16 v[84:87], v[152:155], v[168:171], v[84:87]
	v_mfma_f32_16x16x32_bf16 v[88:91], v[152:155], v[172:175], v[88:91]
	s_add_u32 m0, s15, 0x1e000
	v_mfma_f32_16x16x32_bf16 v[92:95], v[152:155], v[176:179], v[92:95]
	global_load_lds_dwordx4 v144, s[24:25]
	s_add_u32 s10, s10, 0x80
	s_addc_u32 s11, s11, 0
	s_add_u32 s24, s24, 0x80
	s_addc_u32 s25, s25, 0
	s_waitcnt lgkmcnt(3)
	v_mfma_f32_16x16x32_bf16 v[96:99], v[156:159], v[164:167], v[96:99]
	ds_read_b128 v[152:155], v205 offset:2048
	v_mfma_f32_16x16x32_bf16 v[100:103], v[156:159], v[168:171], v[100:103]
	v_mfma_f32_16x16x32_bf16 v[104:107], v[156:159], v[172:175], v[104:107]
	v_mfma_f32_16x16x32_bf16 v[108:111], v[156:159], v[176:179], v[108:111]
	s_waitcnt lgkmcnt(2)
	v_mfma_f32_16x16x32_bf16 v[112:115], v[160:163], v[164:167], v[112:115]
	ds_read_b128 v[156:159], v205 offset:4096
	v_mfma_f32_16x16x32_bf16 v[116:119], v[160:163], v[168:171], v[116:119]
	v_mfma_f32_16x16x32_bf16 v[120:123], v[160:163], v[172:175], v[120:123]
	v_mfma_f32_16x16x32_bf16 v[124:127], v[160:163], v[176:179], v[124:127]
	s_waitcnt lgkmcnt(2)
	v_mfma_f32_16x16x32_bf16 v[0:3], v[148:151], v[180:183], v[0:3]
	ds_read_b128 v[160:163], v205 offset:6144
	v_mfma_f32_16x16x32_bf16 v[4:7], v[148:151], v[184:187], v[4:7]
	v_mfma_f32_16x16x32_bf16 v[8:11], v[148:151], v[196:199], v[8:11]
	v_mfma_f32_16x16x32_bf16 v[12:15], v[148:151], v[200:203], v[12:15]
	s_waitcnt lgkmcnt(2)
	v_mfma_f32_16x16x32_bf16 v[16:19], v[152:155], v[180:183], v[16:19]
	ds_read_b128 v[148:151], v205 offset:8192
	v_mfma_f32_16x16x32_bf16 v[20:23], v[152:155], v[184:187], v[20:23]
	v_mfma_f32_16x16x32_bf16 v[24:27], v[152:155], v[196:199], v[24:27]
	v_mfma_f32_16x16x32_bf16 v[28:31], v[152:155], v[200:203], v[28:31]
	s_waitcnt lgkmcnt(2)
	v_mfma_f32_16x16x32_bf16 v[32:35], v[156:159], v[180:183], v[32:35]
	ds_read_b128 v[152:155], v205 offset:10240
	v_mfma_f32_16x16x32_bf16 v[36:39], v[156:159], v[184:187], v[36:39]
	v_mfma_f32_16x16x32_bf16 v[40:43], v[156:159], v[196:199], v[40:43]
	v_mfma_f32_16x16x32_bf16 v[44:47], v[156:159], v[200:203], v[44:47]
	s_waitcnt lgkmcnt(2)
	v_mfma_f32_16x16x32_bf16 v[48:51], v[160:163], v[180:183], v[48:51]
	ds_read_b128 v[156:159], v205 offset:12288
	v_mfma_f32_16x16x32_bf16 v[52:55], v[160:163], v[184:187], v[52:55]
	v_mfma_f32_16x16x32_bf16 v[56:59], v[160:163], v[196:199], v[56:59]
	v_mfma_f32_16x16x32_bf16 v[60:63], v[160:163], v[200:203], v[60:63]
	s_waitcnt lgkmcnt(2)
	v_mfma_f32_16x16x32_bf16 v[64:67], v[148:151], v[180:183], v[64:67]
	ds_read_b128 v[160:163], v205 offset:14336
	v_mfma_f32_16x16x32_bf16 v[68:71], v[148:151], v[184:187], v[68:71]
	v_mfma_f32_16x16x32_bf16 v[72:75], v[148:151], v[196:199], v[72:75]
	v_mfma_f32_16x16x32_bf16 v[76:79], v[148:151], v[200:203], v[76:79]
	s_waitcnt lgkmcnt(2)
	v_mfma_f32_16x16x32_bf16 v[80:83], v[152:155], v[180:183], v[80:83]
	v_mfma_f32_16x16x32_bf16 v[84:87], v[152:155], v[184:187], v[84:87]
	v_mfma_f32_16x16x32_bf16 v[88:91], v[152:155], v[196:199], v[88:91]
	v_mfma_f32_16x16x32_bf16 v[92:95], v[152:155], v[200:203], v[92:95]
	s_waitcnt lgkmcnt(0)
	s_waitcnt vmcnt(0)
	s_barrier
	v_xor_b32_e32 v204, 0x10000, v204
	v_xor_b32_e32 v205, 0x10000, v205
	v_xor_b32_e32 v220, 0x10000, v220
	v_xor_b32_e32 v221, 0x10000, v221
	v_mfma_f32_16x16x32_bf16 v[96:99], v[156:159], v[180:183], v[96:99]
	ds_read_b128 v[148:151], v204
	ds_read_b128 v[152:155], v204 offset:2048
	v_mfma_f32_16x16x32_bf16 v[100:103], v[156:159], v[184:187], v[100:103]
	v_mfma_f32_16x16x32_bf16 v[104:107], v[156:159], v[196:199], v[104:107]
	ds_read_b128 v[164:167], v220 offset:32768
	ds_read_b128 v[168:171], v220 offset:34816
	v_mfma_f32_16x16x32_bf16 v[108:111], v[156:159], v[200:203], v[108:111]
	v_mfma_f32_16x16x32_bf16 v[112:115], v[160:163], v[180:183], v[112:115]
	ds_read_b128 v[156:159], v204 offset:4096
	v_mfma_f32_16x16x32_bf16 v[116:119], v[160:163], v[184:187], v[116:119]
	ds_read_b128 v[172:175], v220 offset:36864
	ds_read_b128 v[176:179], v220 offset:38912
	v_mfma_f32_16x16x32_bf16 v[120:123], v[160:163], v[196:199], v[120:123]
	v_mfma_f32_16x16x32_bf16 v[124:127], v[160:163], v[200:203], v[124:127]
	s_waitcnt lgkmcnt(4)
	v_mfma_f32_16x16x32_bf16 v[0:3], v[148:151], v[164:167], v[0:3]
	ds_read_b128 v[160:163], v204 offset:6144
	s_waitcnt lgkmcnt(4)
	v_mfma_f32_16x16x32_bf16 v[4:7], v[148:151], v[168:171], v[4:7]
	ds_read_b128 v[180:183], v221 offset:32768
	s_waitcnt lgkmcnt(3)
	v_mfma_f32_16x16x32_bf16 v[8:11], v[148:151], v[172:175], v[8:11]
	s_waitcnt lgkmcnt(2)
	v_mfma_f32_16x16x32_bf16 v[12:15], v[148:151], v[176:179], v[12:15]
	v_mfma_f32_16x16x32_bf16 v[16:19], v[152:155], v[164:167], v[16:19]
	ds_read_b128 v[148:151], v204 offset:8192
	v_mfma_f32_16x16x32_bf16 v[20:23], v[152:155], v[168:171], v[20:23]
	ds_read_b128 v[184:187], v221 offset:34816
	v_mfma_f32_16x16x32_bf16 v[24:27], v[152:155], v[172:175], v[24:27]
	v_mfma_f32_16x16x32_bf16 v[28:31], v[152:155], v[176:179], v[28:31]
	v_mfma_f32_16x16x32_bf16 v[32:35], v[156:159], v[164:167], v[32:35]
	ds_read_b128 v[152:155], v204 offset:10240
	v_mfma_f32_16x16x32_bf16 v[36:39], v[156:159], v[168:171], v[36:39]
	ds_read_b128 v[196:199], v221 offset:36864
	v_mfma_f32_16x16x32_bf16 v[40:43], v[156:159], v[172:175], v[40:43]
	v_mfma_f32_16x16x32_bf16 v[44:47], v[156:159], v[176:179], v[44:47]
	s_waitcnt lgkmcnt(5)
	v_mfma_f32_16x16x32_bf16 v[48:51], v[160:163], v[164:167], v[48:51]
	ds_read_b128 v[156:159], v204 offset:12288
	v_mfma_f32_16x16x32_bf16 v[52:55], v[160:163], v[168:171], v[52:55]
	ds_read_b128 v[200:203], v221 offset:38912
	v_mfma_f32_16x16x32_bf16 v[56:59], v[160:163], v[172:175], v[56:59]
	v_mfma_f32_16x16x32_bf16 v[60:63], v[160:163], v[176:179], v[60:63]
	s_waitcnt lgkmcnt(5)
	v_mfma_f32_16x16x32_bf16 v[64:67], v[148:151], v[164:167], v[64:67]
	ds_read_b128 v[160:163], v204 offset:14336
	v_mfma_f32_16x16x32_bf16 v[68:71], v[148:151], v[168:171], v[68:71]
	v_mfma_f32_16x16x32_bf16 v[72:75], v[148:151], v[172:175], v[72:75]
	v_mfma_f32_16x16x32_bf16 v[76:79], v[148:151], v[176:179], v[76:79]
	s_waitcnt lgkmcnt(4)
	v_mfma_f32_16x16x32_bf16 v[80:83], v[152:155], v[164:167], v[80:83]
	ds_read_b128 v[148:151], v205
	v_mfma_f32_16x16x32_bf16 v[84:87], v[152:155], v[168:171], v[84:87]
	v_mfma_f32_16x16x32_bf16 v[88:91], v[152:155], v[172:175], v[88:91]
	v_mfma_f32_16x16x32_bf16 v[92:95], v[152:155], v[176:179], v[92:95]
	s_waitcnt lgkmcnt(3)
	v_mfma_f32_16x16x32_bf16 v[96:99], v[156:159], v[164:167], v[96:99]
	ds_read_b128 v[152:155], v205 offset:2048
	v_mfma_f32_16x16x32_bf16 v[100:103], v[156:159], v[168:171], v[100:103]
	v_mfma_f32_16x16x32_bf16 v[104:107], v[156:159], v[172:175], v[104:107]
	v_mfma_f32_16x16x32_bf16 v[108:111], v[156:159], v[176:179], v[108:111]
	s_waitcnt lgkmcnt(2)
	v_mfma_f32_16x16x32_bf16 v[112:115], v[160:163], v[164:167], v[112:115]
	ds_read_b128 v[156:159], v205 offset:4096
	v_mfma_f32_16x16x32_bf16 v[116:119], v[160:163], v[168:171], v[116:119]
	v_mfma_f32_16x16x32_bf16 v[120:123], v[160:163], v[172:175], v[120:123]
	v_mfma_f32_16x16x32_bf16 v[124:127], v[160:163], v[176:179], v[124:127]
	s_waitcnt lgkmcnt(2)
	v_mfma_f32_16x16x32_bf16 v[0:3], v[148:151], v[180:183], v[0:3]
	ds_read_b128 v[160:163], v205 offset:6144
	v_mfma_f32_16x16x32_bf16 v[4:7], v[148:151], v[184:187], v[4:7]
	v_mfma_f32_16x16x32_bf16 v[8:11], v[148:151], v[196:199], v[8:11]
	v_mfma_f32_16x16x32_bf16 v[12:15], v[148:151], v[200:203], v[12:15]
	s_waitcnt lgkmcnt(2)
	v_mfma_f32_16x16x32_bf16 v[16:19], v[152:155], v[180:183], v[16:19]
	ds_read_b128 v[148:151], v205 offset:8192
	v_mfma_f32_16x16x32_bf16 v[20:23], v[152:155], v[184:187], v[20:23]
	v_mfma_f32_16x16x32_bf16 v[24:27], v[152:155], v[196:199], v[24:27]
	v_mfma_f32_16x16x32_bf16 v[28:31], v[152:155], v[200:203], v[28:31]
	s_waitcnt lgkmcnt(2)
	v_mfma_f32_16x16x32_bf16 v[32:35], v[156:159], v[180:183], v[32:35]
	ds_read_b128 v[152:155], v205 offset:10240
	v_mfma_f32_16x16x32_bf16 v[36:39], v[156:159], v[184:187], v[36:39]
	v_mfma_f32_16x16x32_bf16 v[40:43], v[156:159], v[196:199], v[40:43]
	v_mfma_f32_16x16x32_bf16 v[44:47], v[156:159], v[200:203], v[44:47]
	s_waitcnt lgkmcnt(2)
	v_mfma_f32_16x16x32_bf16 v[48:51], v[160:163], v[180:183], v[48:51]
	ds_read_b128 v[156:159], v205 offset:12288
	v_mfma_f32_16x16x32_bf16 v[52:55], v[160:163], v[184:187], v[52:55]
	v_mfma_f32_16x16x32_bf16 v[56:59], v[160:163], v[196:199], v[56:59]
	v_mfma_f32_16x16x32_bf16 v[60:63], v[160:163], v[200:203], v[60:63]
	s_waitcnt lgkmcnt(2)
	v_mfma_f32_16x16x32_bf16 v[64:67], v[148:151], v[180:183], v[64:67]
	ds_read_b128 v[160:163], v205 offset:14336
	v_mfma_f32_16x16x32_bf16 v[68:71], v[148:151], v[184:187], v[68:71]
	v_mfma_f32_16x16x32_bf16 v[72:75], v[148:151], v[196:199], v[72:75]
	v_mfma_f32_16x16x32_bf16 v[76:79], v[148:151], v[200:203], v[76:79]
	s_waitcnt lgkmcnt(2)
	v_mfma_f32_16x16x32_bf16 v[80:83], v[152:155], v[180:183], v[80:83]
	v_mfma_f32_16x16x32_bf16 v[84:87], v[152:155], v[184:187], v[84:87]
	v_mfma_f32_16x16x32_bf16 v[88:91], v[152:155], v[196:199], v[88:91]
	v_mfma_f32_16x16x32_bf16 v[92:95], v[152:155], v[200:203], v[92:95]
	s_waitcnt lgkmcnt(0)
	s_waitcnt vmcnt(0)
	s_barrier
	v_xor_b32_e32 v204, 0x10000, v204
	v_xor_b32_e32 v205, 0x10000, v205
	v_xor_b32_e32 v220, 0x10000, v220
	v_xor_b32_e32 v221, 0x10000, v221
	v_mfma_f32_16x16x32_bf16 v[96:99], v[156:159], v[180:183], v[96:99]
	v_mfma_f32_16x16x32_bf16 v[100:103], v[156:159], v[184:187], v[100:103]
	v_mfma_f32_16x16x32_bf16 v[104:107], v[156:159], v[196:199], v[104:107]
	v_mfma_f32_16x16x32_bf16 v[108:111], v[156:159], v[200:203], v[108:111]
	v_mfma_f32_16x16x32_bf16 v[112:115], v[160:163], v[180:183], v[112:115]
	v_mfma_f32_16x16x32_bf16 v[116:119], v[160:163], v[184:187], v[116:119]
	v_mfma_f32_16x16x32_bf16 v[120:123], v[160:163], v[196:199], v[120:123]
	v_mfma_f32_16x16x32_bf16 v[124:127], v[160:163], v[200:203], v[124:127]
	s_mov_b32 m0, s26
	v_lshlrev_b32_e32 v192, 2, v147
	v_ashrrev_i32_e32 v142, 8, v146
	v_readlane_b32 s0, v254, 11
	s_nop 3
	s_add_u32 s0, s4, s0
	s_addc_u32 s1, s5, 0
	s_mov_b32 s4, 0
	s_mov_b64 s[2:3], -1
	v_lshl_add_u32 v148, v142, 7, s28
	v_ashrrev_i32_e32 v149, 31, v148
	v_mul_i32_i24_e32 v150, 0x10c00, v142
	v_lshl_add_u64 v[130:131], v[148:149], 2, s[0:1]
	v_lshl_add_u64 v[132:133], v[148:149], 1, v[128:129]
	s_mov_b64 s[0:1], 0x1408e000
	v_lshl_add_u64 v[128:129], v[132:133], 0, s[0:1]
	v_lshl_add_u64 v[130:131], v[130:131], 0, v[192:193]
	s_mov_b64 s[0:1], 0x14012000
	v_lshl_add_u64 v[130:131], v[130:131], 0, s[0:1]
	s_mov_b64 s[0:1], 0x1708e000
	v_lshl_add_u64 v[132:133], v[132:133], 0, s[0:1]
	v_bfe_u32 v135, v146, 5, 3
	v_readlane_b32 s0, v254, 23
	v_and_b32_e32 v136, 31, v146
	v_lshlrev_b32_e32 v136, 4, v136
	s_nop 1
	v_add_u32_e32 v134, s0, v135
	s_nop 7
	s_nop 3
	v_mul_u32_u24_e32 v135, 0x210, v135
	v_add3_u32 v135, v150, v135, v136
.LBB0_509:
	v_mov_b32_e32 v136, v195
	s_nop 0
	v_ashrrev_i32_e32 v137, 8, v136
	v_cmp_eq_u32_e32 vcc, s4, v137
	s_and_saveexec_b64 s[0:1], vcc
	s_cbranch_execz .LBB0_511
	v_bfe_i32 v137, v195, 7, 1
	v_and_b32_e32 v137, 0x10c00, v137
	v_and_b32_e32 v138, 0x4f, v195
	v_lshl_or_b32 v137, v138, 2, v137
	v_bfe_u32 v136, v195, 4, 2
	v_mul_u32_u24_e32 v136, 0x840, v136
	v_add_u32_e32 v136, v136, v137
	v_mov_b32_e32 v137, v136
	v_add_u32_e32 v138, 0x420, v136
	ds_write2_b32 v137, v0, v1 offset1:132
	ds_write2_b32 v138, v2, v3 offset1:132
	ds_write2_b32 v137, v4, v5 offset0:16 offset1:148
	ds_write2_b32 v138, v6, v7 offset0:16 offset1:148
	ds_write2_b32 v137, v8, v9 offset0:32 offset1:164
	ds_write2_b32 v138, v10, v11 offset0:32 offset1:164
	ds_write2_b32 v137, v12, v13 offset0:48 offset1:180
	ds_write2_b32 v138, v14, v15 offset0:48 offset1:180
	v_add_u32_e32 v137, 0x2100, v136
	v_add_u32_e32 v138, 0x2520, v136
	ds_write2_b32 v137, v16, v17 offset1:132
	ds_write2_b32 v138, v18, v19 offset1:132
	ds_write2_b32 v137, v20, v21 offset0:16 offset1:148
	ds_write2_b32 v138, v22, v23 offset0:16 offset1:148
	ds_write2_b32 v137, v24, v25 offset0:32 offset1:164
	ds_write2_b32 v138, v26, v27 offset0:32 offset1:164
	ds_write2_b32 v137, v28, v29 offset0:48 offset1:180
	ds_write2_b32 v138, v30, v31 offset0:48 offset1:180
	v_add_u32_e32 v137, 0x4200, v136
	v_add_u32_e32 v138, 0x4620, v136
	ds_write2_b32 v137, v32, v33 offset1:132
	ds_write2_b32 v138, v34, v35 offset1:132
	ds_write2_b32 v137, v36, v37 offset0:16 offset1:148
	ds_write2_b32 v138, v38, v39 offset0:16 offset1:148
	ds_write2_b32 v137, v40, v41 offset0:32 offset1:164
	ds_write2_b32 v138, v42, v43 offset0:32 offset1:164
	ds_write2_b32 v137, v44, v45 offset0:48 offset1:180
	ds_write2_b32 v138, v46, v47 offset0:48 offset1:180
	v_add_u32_e32 v137, 0x6300, v136
	v_add_u32_e32 v138, 0x6720, v136
	ds_write2_b32 v137, v48, v49 offset1:132
	ds_write2_b32 v138, v50, v51 offset1:132
	ds_write2_b32 v137, v52, v53 offset0:16 offset1:148
	ds_write2_b32 v138, v54, v55 offset0:16 offset1:148
	ds_write2_b32 v137, v56, v57 offset0:32 offset1:164
	ds_write2_b32 v138, v58, v59 offset0:32 offset1:164
	ds_write2_b32 v137, v60, v61 offset0:48 offset1:180
	ds_write2_b32 v138, v62, v63 offset0:48 offset1:180
	v_add_u32_e32 v137, 0x8400, v136
	v_add_u32_e32 v138, 0x8820, v136
	ds_write2_b32 v137, v64, v65 offset1:132
	ds_write2_b32 v138, v66, v67 offset1:132
	ds_write2_b32 v137, v68, v69 offset0:16 offset1:148
	ds_write2_b32 v138, v70, v71 offset0:16 offset1:148
	ds_write2_b32 v137, v72, v73 offset0:32 offset1:164
	ds_write2_b32 v138, v74, v75 offset0:32 offset1:164
	ds_write2_b32 v137, v76, v77 offset0:48 offset1:180
	ds_write2_b32 v138, v78, v79 offset0:48 offset1:180
	v_add_u32_e32 v137, 0xa500, v136
	v_add_u32_e32 v138, 0xa920, v136
	ds_write2_b32 v137, v80, v81 offset1:132
	ds_write2_b32 v138, v82, v83 offset1:132
	ds_write2_b32 v137, v84, v85 offset0:16 offset1:148
	ds_write2_b32 v138, v86, v87 offset0:16 offset1:148
	ds_write2_b32 v137, v88, v89 offset0:32 offset1:164
	ds_write2_b32 v138, v90, v91 offset0:32 offset1:164
	ds_write2_b32 v137, v92, v93 offset0:48 offset1:180
	ds_write2_b32 v138, v94, v95 offset0:48 offset1:180
	v_add_u32_e32 v137, 0xc600, v136
	v_add_u32_e32 v138, 0xca20, v136
	ds_write2_b32 v137, v96, v97 offset1:132
	ds_write2_b32 v138, v98, v99 offset1:132
	ds_write2_b32 v137, v100, v101 offset0:16 offset1:148
	ds_write2_b32 v138, v102, v103 offset0:16 offset1:148
	ds_write2_b32 v137, v104, v105 offset0:32 offset1:164
	ds_write2_b32 v138, v106, v107 offset0:32 offset1:164
	ds_write2_b32 v137, v108, v109 offset0:48 offset1:180
	ds_write2_b32 v138, v110, v111 offset0:48 offset1:180
	v_add_u32_e32 v137, 0xe700, v136
	v_add_u32_e32 v138, 0xeb20, v136
	ds_write2_b32 v137, v112, v113 offset1:132
	ds_write2_b32 v138, v114, v115 offset1:132
	ds_write2_b32 v137, v116, v117 offset0:16 offset1:148
	ds_write2_b32 v138, v118, v119 offset0:16 offset1:148
	ds_write2_b32 v137, v120, v121 offset0:32 offset1:164
	ds_write2_b32 v138, v122, v123 offset0:32 offset1:164
	ds_write2_b32 v137, v124, v125 offset0:48 offset1:180
	ds_write2_b32 v138, v126, v127 offset0:48 offset1:180
